# MLA: waves 4-7 meet the barrier behind their 1st PV MFMA (tile writes in front of it)
# baseline (speedup 1.0000x reference)
; __device__ __forceinline__ void finishSM9(f32x16& p0, f32x16& p1, float alpha, float& l_reg, v8i32& p8) {
; #pragma unroll
;   for (int r = 0; r < 16; ++r) { p0[r] = __builtin_amdgcn_exp2f(p0[r]); p1[r] = __builtin_amdgcn_exp2f(p1[r]); }
;   float ps = 0;
; #pragma unroll
;   for (int r = 0; r < 16; ++r) ps += p0[r];
; #pragma unroll
;   for (int r = 0; r < 16; ++r) ps += p1[r];
;   { auto rr = __builtin_amdgcn_permlane32_swap(__float_as_uint(ps), __float_as_uint(ps), false, false);
;     ps = __uint_as_float(rr[0]) + __uint_as_float(rr[1]); }
;   l_reg = l_reg * alpha + ps;
; #pragma unroll
;   for (int g = 0; g < 4; ++g) {
;     int w = __builtin_amdgcn_cvt_pk_fp8_f32(p0[4 * g], p0[4 * g + 1], 0, false); p8[g] = __builtin_amdgcn_cvt_pk_fp8_f32(p0[4 * g + 2], p0[4 * g + 3], w, true);
;     int u = __builtin_amdgcn_cvt_pk_fp8_f32(p1[4 * g], p1[4 * g + 1], 0, false); p8[4 + g] = __builtin_amdgcn_cvt_pk_fp8_f32(p1[4 * g + 2], p1[4 * g + 3], u, true); }
; }
; __device__ __forceinline__ void pv8(f32x16* o, const char* Vt, const v8i32 p8, int r32, int hi) {
;   const int sw = (r32 >> 2) & 3, a0 = r32 * 64 + (((hi * 2) ^ sw) << 4), a1 = r32 * 64 + (((hi * 2 + 1) ^ sw) << 4);
; #pragma unroll
;   for (int d0 = 0; d0 < 4; ++d0) {
;     const v8i32 vf = cat8(*reinterpret_cast<const v4i32*>(Vt + d0 * 2048 + a0), *reinterpret_cast<const v4i32*>(Vt + d0 * 2048 + a1));
;     o[d0] = __builtin_amdgcn_mfma_scale_f32_32x32x64_f8f6f4(p8, vf, o[d0], 0, 0, 0, 127, 0, 127); }
; }
; __device__ __forceinline__ void qkt9(f32x16& p0, f32x16& p1, const char* Kn, const char* Kr, const v8i32* qf, const float init, int r32, int hi) {
; #pragma unroll
;   for (int r = 0; r < 16; ++r) { p0[r] = init; p1[r] = init; }
; #pragma unroll
;   for (int s = 0; s < 2; ++s) { const int c0 = s * 4 + hi * 2;
;     const v8i32 a0 = cat8(*reinterpret_cast<const v4i32*>(Kn + KN8SW(r32, c0)), *reinterpret_cast<const v4i32*>(Kn + KN8SW(r32, c0 + 1)));
;     const v8i32 a1 = cat8(*reinterpret_cast<const v4i32*>(Kn + 4096 + KN8SW(r32, c0)), *reinterpret_cast<const v4i32*>(Kn + 4096 + KN8SW(r32, c0 + 1)));
;     p0 = __builtin_amdgcn_mfma_scale_f32_32x32x64_f8f6f4(a0, qf[s], p0, 0, 0, 0, 127, 0, 124);
;     p1 = __builtin_amdgcn_mfma_scale_f32_32x32x64_f8f6f4(a1, qf[s], p1, 0, 0, 0, 127, 0, 124); }
;   { const int c0 = hi * 2;
.Lmla_stag_loop:
	ds_read_b128 v[114:117], v215 offset:24576
	ds_read_b128 v[118:121], v216 offset:24576
	ds_read_b128 v[222:225], v215 offset:28672
	ds_read_b128 v[226:229], v216 offset:28672
	v_exp_f32_e32 v0, v82
	v_exp_f32_e32 v177, v83
	v_exp_f32_e32 v179, v84
	v_exp_f32_e32 v254, v85
	v_add_f32_e32 v219, v0, v177
	v_cvt_pk_fp8_f32 v246, v0, v177
	v_add_f32_e32 v219, v179, v219
	v_add_f32_e32 v219, v254, v219
	v_cvt_pk_fp8_f32 v246, v179, v254 op_sel:[0,0,1]
	s_waitcnt lgkmcnt(2)
	v_mfma_scale_f32_32x32x64_f8f6f4 v[114:129], v[114:121], v[146:153], v[230:245], v194, v193 op_sel_hi:[0,0,0]
	v_exp_f32_e32 v0, v86
	v_exp_f32_e32 v177, v87
	v_exp_f32_e32 v179, v88
	v_exp_f32_e32 v254, v89
	v_add_f32_e32 v219, v0, v219
	v_add_f32_e32 v219, v177, v219
	v_cvt_pk_fp8_f32 v247, v0, v177
	v_add_f32_e32 v219, v179, v219
	v_add_f32_e32 v219, v254, v219
	v_cvt_pk_fp8_f32 v247, v179, v254 op_sel:[0,0,1]
	ds_read_b128 v[82:85], v213 offset:24576
	ds_read_b128 v[86:89], v214 offset:24576
	s_waitcnt lgkmcnt(2)
	v_mfma_scale_f32_32x32x64_f8f6f4 v[98:113], v[222:229], v[146:153], v[230:245], v194, v193 op_sel_hi:[0,0,0]
	ds_read_b128 v[222:225], v213 offset:28672
	ds_read_b128 v[226:229], v214 offset:28672
	v_exp_f32_e32 v0, v90
	v_exp_f32_e32 v177, v91
	v_exp_f32_e32 v179, v92
	v_exp_f32_e32 v254, v93
	v_add_f32_e32 v219, v0, v219
	v_add_f32_e32 v219, v177, v219
	v_cvt_pk_fp8_f32 v248, v0, v177
	v_add_f32_e32 v219, v179, v219
	v_add_f32_e32 v219, v254, v219
	v_cvt_pk_fp8_f32 v248, v179, v254 op_sel:[0,0,1]
	v_exp_f32_e32 v0, v94
	v_exp_f32_e32 v177, v95
	v_exp_f32_e32 v179, v96
	v_exp_f32_e32 v254, v97
	v_add_f32_e32 v219, v0, v219
	v_add_f32_e32 v219, v177, v219
	v_cvt_pk_fp8_f32 v249, v0, v177
	v_add_f32_e32 v219, v179, v219
	v_add_f32_e32 v219, v254, v219
	v_cvt_pk_fp8_f32 v249, v179, v254 op_sel:[0,0,1]
	ds_read_b128 v[90:93], v185 offset:36864
	ds_read_b128 v[94:97], v186 offset:36864
	s_waitcnt lgkmcnt(4)
	v_mfma_scale_f32_32x32x64_f8f6f4 v[114:129], v[82:89], v[138:145], v[114:129], v194, v193 op_sel_hi:[0,0,0]
	v_exp_f32_e32 v0, v66
	v_exp_f32_e32 v177, v67
	v_exp_f32_e32 v179, v68
	v_exp_f32_e32 v254, v69
	v_add_f32_e32 v219, v0, v219
	v_add_f32_e32 v219, v177, v219
	v_cvt_pk_fp8_f32 v250, v0, v177
	v_add_f32_e32 v219, v179, v219
	v_add_f32_e32 v219, v254, v219
	v_cvt_pk_fp8_f32 v250, v179, v254 op_sel:[0,0,1]
	s_waitcnt lgkmcnt(2)
	v_mfma_scale_f32_32x32x64_f8f6f4 v[98:113], v[222:229], v[138:145], v[98:113], v194, v193 op_sel_hi:[0,0,0]
	ds_read_b128 v[222:225], v185 offset:38912
	ds_read_b128 v[226:229], v186 offset:38912
	v_exp_f32_e32 v0, v70
	v_exp_f32_e32 v177, v71
	v_exp_f32_e32 v179, v72
	v_exp_f32_e32 v254, v73
	v_add_f32_e32 v219, v0, v219
	v_add_f32_e32 v219, v177, v219
	v_cvt_pk_fp8_f32 v251, v0, v177
	v_add_f32_e32 v219, v179, v219
	v_add_f32_e32 v219, v254, v219
	v_cvt_pk_fp8_f32 v251, v179, v254 op_sel:[0,0,1]
	v_exp_f32_e32 v0, v74
	v_exp_f32_e32 v177, v75
	v_exp_f32_e32 v179, v76
	v_exp_f32_e32 v254, v77
	v_add_f32_e32 v219, v0, v219
	v_add_f32_e32 v219, v177, v219
	v_cvt_pk_fp8_f32 v252, v0, v177
	v_add_f32_e32 v219, v179, v219
	v_add_f32_e32 v219, v254, v219
	v_cvt_pk_fp8_f32 v252, v179, v254 op_sel:[0,0,1]
	s_waitcnt lgkmcnt(2)
	v_mfma_scale_f32_32x32x64_f8f6f4 v[114:129], v[90:97], v[130:137], v[114:129], v194, v193 op_sel_hi:[0,0,0]
	v_exp_f32_e32 v0, v78
	v_exp_f32_e32 v177, v79
	v_exp_f32_e32 v179, v80
	v_exp_f32_e32 v254, v81
	v_add_f32_e32 v219, v0, v219
	v_add_f32_e32 v219, v177, v219
	v_cvt_pk_fp8_f32 v253, v0, v177
	v_add_f32_e32 v219, v179, v219
	v_add_f32_e32 v219, v254, v219
	v_cvt_pk_fp8_f32 v253, v179, v254 op_sel:[0,0,1]
	ds_read_b128 v[90:93], v185 offset:0
	ds_read_b128 v[94:97], v186 offset:0
	ds_read_b128 v[82:85], v185 offset:2048
	ds_read_b128 v[86:89], v186 offset:2048
	ds_read_b128 v[74:77], v185 offset:4096
	ds_read_b128 v[78:81], v186 offset:4096
	ds_read_b128 v[66:69], v185 offset:6144
	ds_read_b128 v[70:73], v186 offset:6144
	s_waitcnt lgkmcnt(8)
	v_mfma_scale_f32_32x32x64_f8f6f4 v[98:113], v[222:229], v[130:137], v[98:113], v194, v193 op_sel_hi:[0,0,0]
	v_mov_b32_e32 v0, v219
	s_nop 1
	v_permlane32_swap_b32_e32 v219, v0
	v_add_f32_e32 v219, v219, v0
	v_fma_f32 v209, v209, v218, v219
	v_max_f32_e32 v177, v114, v115
	v_max3_f32 v177, v177, v116, v117
	v_max3_f32 v177, v177, v118, v119
	v_max3_f32 v177, v177, v120, v121
	v_max3_f32 v177, v177, v122, v123
	v_max3_f32 v177, v177, v124, v125
	v_max3_f32 v177, v177, v126, v127
	v_max3_f32 v177, v177, v128, v129
	s_waitcnt vmcnt(0)
	ds_write_b128 v210, v[158:161] offset:43008
	ds_write_b128 v211, v[162:165] offset:51200
	s_waitcnt lgkmcnt(8)
	v_mfma_scale_f32_32x32x64_f8f6f4 v[50:65], v[246:253], v[90:97], v[50:65], v194, v194 op_sel_hi:[0,0,0]
	s_waitcnt lgkmcnt(0)
	s_barrier
	global_load_dwordx4 v[158:161], v176, s[18:19]
	global_load_dwordx4 v[162:165], v178, s[16:17]
	v_add_u32_e32 v176, 0x2000, v176
	v_add_u32_e32 v178, 0x20000, v178
	s_waitcnt lgkmcnt(4)
	v_mfma_scale_f32_32x32x64_f8f6f4 v[34:49], v[246:253], v[82:89], v[34:49], v194, v194 op_sel_hi:[0,0,0]
	s_waitcnt lgkmcnt(2)
	v_mfma_scale_f32_32x32x64_f8f6f4 v[18:33], v[246:253], v[74:81], v[18:33], v194, v194 op_sel_hi:[0,0,0]
	s_waitcnt lgkmcnt(0)
	v_mfma_scale_f32_32x32x64_f8f6f4 v[2:17], v[246:253], v[66:73], v[2:17], v194, v194 op_sel_hi:[0,0,0]
	v_max_f32_e32 v0, v98, v99
	v_max3_f32 v0, v0, v100, v101
	v_max3_f32 v0, v0, v102, v103
	v_max3_f32 v0, v0, v104, v105
	v_max3_f32 v0, v0, v106, v107
	v_max3_f32 v0, v0, v108, v109
	v_max3_f32 v0, v0, v110, v111
	v_max3_f32 v0, v0, v112, v113
	v_max_f32_e32 v177, v177, v0
	v_mov_b32_e32 v0, v177
	v_mov_b32_e32 v221, 1.0
	s_nop 0
	v_permlane32_swap_b32_e32 v177, v0
	v_max_f32_e32 v177, v177, v0
	v_cmp_ge_f32_e32 vcc, s90, v177
	s_cmp_eq_u64 vcc, exec
	s_cbranch_scc0 .Lmla_s0_newmax
; __device__ __forceinline__ void finishSM9(f32x16& p0, f32x16& p1, float alpha, float& l_reg, v8i32& p8) {
; #pragma unroll
;   for (int r = 0; r < 16; ++r) { p0[r] = __builtin_amdgcn_exp2f(p0[r]); p1[r] = __builtin_amdgcn_exp2f(p1[r]); }
;   float ps = 0;
; #pragma unroll
;   for (int r = 0; r < 16; ++r) ps += p0[r];
; #pragma unroll
;   for (int r = 0; r < 16; ++r) ps += p1[r];
;   { auto rr = __builtin_amdgcn_permlane32_swap(__float_as_uint(ps), __float_as_uint(ps), false, false);
;     ps = __uint_as_float(rr[0]) + __uint_as_float(rr[1]); }
;   l_reg = l_reg * alpha + ps;
; #pragma unroll
;   for (int g = 0; g < 4; ++g) {
;     int w = __builtin_amdgcn_cvt_pk_fp8_f32(p0[4 * g], p0[4 * g + 1], 0, false); p8[g] = __builtin_amdgcn_cvt_pk_fp8_f32(p0[4 * g + 2], p0[4 * g + 3], w, true);
;     int u = __builtin_amdgcn_cvt_pk_fp8_f32(p1[4 * g], p1[4 * g + 1], 0, false); p8[4 + g] = __builtin_amdgcn_cvt_pk_fp8_f32(p1[4 * g + 2], p1[4 * g + 3], u, true); }
; }
; __device__ __forceinline__ void pv8(f32x16* o, const char* Vt, const v8i32 p8, int r32, int hi) {
;   const int sw = (r32 >> 2) & 3, a0 = r32 * 64 + (((hi * 2) ^ sw) << 4), a1 = r32 * 64 + (((hi * 2 + 1) ^ sw) << 4);
; #pragma unroll
;   for (int d0 = 0; d0 < 4; ++d0) {
;     const v8i32 vf = cat8(*reinterpret_cast<const v4i32*>(Vt + d0 * 2048 + a0), *reinterpret_cast<const v4i32*>(Vt + d0 * 2048 + a1));
;     o[d0] = __builtin_amdgcn_mfma_scale_f32_32x32x64_f8f6f4(p8, vf, o[d0], 0, 0, 0, 127, 0, 127); }
; }
; __device__ __forceinline__ void qkt9(f32x16& p0, f32x16& p1, const char* Kn, const char* Kr, const v8i32* qf, const float init, int r32, int hi) {
; #pragma unroll
;   for (int r = 0; r < 16; ++r) { p0[r] = init; p1[r] = init; }
; #pragma unroll
;   for (int s = 0; s < 2; ++s) { const int c0 = s * 4 + hi * 2;
;     const v8i32 a0 = cat8(*reinterpret_cast<const v4i32*>(Kn + KN8SW(r32, c0)), *reinterpret_cast<const v4i32*>(Kn + KN8SW(r32, c0 + 1)));
;     const v8i32 a1 = cat8(*reinterpret_cast<const v4i32*>(Kn + 4096 + KN8SW(r32, c0)), *reinterpret_cast<const v4i32*>(Kn + 4096 + KN8SW(r32, c0 + 1)));
;     p0 = __builtin_amdgcn_mfma_scale_f32_32x32x64_f8f6f4(a0, qf[s], p0, 0, 0, 0, 127, 0, 124);
;     p1 = __builtin_amdgcn_mfma_scale_f32_32x32x64_f8f6f4(a1, qf[s], p1, 0, 0, 0, 127, 0, 124); }
;   { const int c0 = hi * 2;
.Lmla_s0_cont:
	ds_read_b128 v[82:85], v215 offset:51200
	ds_read_b128 v[86:89], v216 offset:51200
	ds_read_b128 v[222:225], v215 offset:55296
	ds_read_b128 v[226:229], v216 offset:55296
	v_exp_f32_e32 v0, v114
	v_exp_f32_e32 v177, v115
	v_exp_f32_e32 v179, v116
	v_exp_f32_e32 v254, v117
	v_add_f32_e32 v219, v0, v177
	v_cvt_pk_fp8_f32 v246, v0, v177
	v_add_f32_e32 v219, v179, v219
	v_add_f32_e32 v219, v254, v219
	v_cvt_pk_fp8_f32 v246, v179, v254 op_sel:[0,0,1]
	s_waitcnt lgkmcnt(2)
	v_mfma_scale_f32_32x32x64_f8f6f4 v[82:97], v[82:89], v[146:153], v[230:245], v194, v193 op_sel_hi:[0,0,0]
	v_exp_f32_e32 v0, v118
	v_exp_f32_e32 v177, v119
	v_exp_f32_e32 v179, v120
	v_exp_f32_e32 v254, v121
	v_add_f32_e32 v219, v0, v219
	v_add_f32_e32 v219, v177, v219
	v_cvt_pk_fp8_f32 v247, v0, v177
	v_add_f32_e32 v219, v179, v219
	v_add_f32_e32 v219, v254, v219
	v_cvt_pk_fp8_f32 v247, v179, v254 op_sel:[0,0,1]
	ds_read_b128 v[114:117], v213 offset:51200
	ds_read_b128 v[118:121], v214 offset:51200
	s_waitcnt lgkmcnt(2)
	v_mfma_scale_f32_32x32x64_f8f6f4 v[66:81], v[222:229], v[146:153], v[230:245], v194, v193 op_sel_hi:[0,0,0]
	ds_read_b128 v[222:225], v213 offset:55296
	ds_read_b128 v[226:229], v214 offset:55296
	v_exp_f32_e32 v0, v122
	v_exp_f32_e32 v177, v123
	v_exp_f32_e32 v179, v124
	v_exp_f32_e32 v254, v125
	v_add_f32_e32 v219, v0, v219
	v_add_f32_e32 v219, v177, v219
	v_cvt_pk_fp8_f32 v248, v0, v177
	v_add_f32_e32 v219, v179, v219
	v_add_f32_e32 v219, v254, v219
	v_cvt_pk_fp8_f32 v248, v179, v254 op_sel:[0,0,1]
	v_exp_f32_e32 v0, v126
	v_exp_f32_e32 v177, v127
	v_exp_f32_e32 v179, v128
	v_exp_f32_e32 v254, v129
	v_add_f32_e32 v219, v0, v219
	v_add_f32_e32 v219, v177, v219
	v_cvt_pk_fp8_f32 v249, v0, v177
	v_add_f32_e32 v219, v179, v219
	v_add_f32_e32 v219, v254, v219
	v_cvt_pk_fp8_f32 v249, v179, v254 op_sel:[0,0,1]
	ds_read_b128 v[122:125], v185 offset:59392
	ds_read_b128 v[126:129], v186 offset:59392
	s_waitcnt lgkmcnt(4)
	v_mfma_scale_f32_32x32x64_f8f6f4 v[82:97], v[114:121], v[138:145], v[82:97], v194, v193 op_sel_hi:[0,0,0]
	v_exp_f32_e32 v0, v98
	v_exp_f32_e32 v177, v99
	v_exp_f32_e32 v179, v100
	v_exp_f32_e32 v254, v101
	v_add_f32_e32 v219, v0, v219
	v_add_f32_e32 v219, v177, v219
	v_cvt_pk_fp8_f32 v250, v0, v177
	v_add_f32_e32 v219, v179, v219
	v_add_f32_e32 v219, v254, v219
	v_cvt_pk_fp8_f32 v250, v179, v254 op_sel:[0,0,1]
	s_waitcnt lgkmcnt(2)
	v_mfma_scale_f32_32x32x64_f8f6f4 v[66:81], v[222:229], v[138:145], v[66:81], v194, v193 op_sel_hi:[0,0,0]
	ds_read_b128 v[222:225], v185 offset:61440
	ds_read_b128 v[226:229], v186 offset:61440
	v_exp_f32_e32 v0, v102
	v_exp_f32_e32 v177, v103
	v_exp_f32_e32 v179, v104
	v_exp_f32_e32 v254, v105
	v_add_f32_e32 v219, v0, v219
	v_add_f32_e32 v219, v177, v219
	v_cvt_pk_fp8_f32 v251, v0, v177
	v_add_f32_e32 v219, v179, v219
	v_add_f32_e32 v219, v254, v219
	v_cvt_pk_fp8_f32 v251, v179, v254 op_sel:[0,0,1]
	v_exp_f32_e32 v0, v106
	v_exp_f32_e32 v177, v107
	v_exp_f32_e32 v179, v108
	v_exp_f32_e32 v254, v109
	v_add_f32_e32 v219, v0, v219
	v_add_f32_e32 v219, v177, v219
	v_cvt_pk_fp8_f32 v252, v0, v177
	v_add_f32_e32 v219, v179, v219
	v_add_f32_e32 v219, v254, v219
	v_cvt_pk_fp8_f32 v252, v179, v254 op_sel:[0,0,1]
	s_waitcnt lgkmcnt(2)
	v_mfma_scale_f32_32x32x64_f8f6f4 v[82:97], v[122:129], v[130:137], v[82:97], v194, v193 op_sel_hi:[0,0,0]
	v_exp_f32_e32 v0, v110
	v_exp_f32_e32 v177, v111
	v_exp_f32_e32 v179, v112
	v_exp_f32_e32 v254, v113
	v_add_f32_e32 v219, v0, v219
	v_add_f32_e32 v219, v177, v219
	v_cvt_pk_fp8_f32 v253, v0, v177
	v_add_f32_e32 v219, v179, v219
	v_add_f32_e32 v219, v254, v219
	v_cvt_pk_fp8_f32 v253, v179, v254 op_sel:[0,0,1]
	ds_read_b128 v[122:125], v185 offset:8192
	ds_read_b128 v[126:129], v186 offset:8192
	ds_read_b128 v[114:117], v185 offset:10240
	ds_read_b128 v[118:121], v186 offset:10240
	ds_read_b128 v[106:109], v185 offset:12288
	ds_read_b128 v[110:113], v186 offset:12288
	ds_read_b128 v[98:101], v185 offset:14336
	ds_read_b128 v[102:105], v186 offset:14336
	s_waitcnt lgkmcnt(8)
	v_mfma_scale_f32_32x32x64_f8f6f4 v[66:81], v[222:229], v[130:137], v[66:81], v194, v193 op_sel_hi:[0,0,0]
	v_mov_b32_e32 v0, v219
	s_nop 1
	v_permlane32_swap_b32_e32 v219, v0
	v_add_f32_e32 v219, v219, v0
	v_fma_f32 v209, v209, v221, v219
	v_max_f32_e32 v177, v82, v83
	v_max3_f32 v177, v177, v84, v85
	v_max3_f32 v177, v177, v86, v87
	v_max3_f32 v177, v177, v88, v89
	v_max3_f32 v177, v177, v90, v91
	v_max3_f32 v177, v177, v92, v93
	v_max3_f32 v177, v177, v94, v95
	v_max3_f32 v177, v177, v96, v97
	s_waitcnt vmcnt(0)
	ds_write_b128 v210, v[158:161]
	ds_write_b128 v211, v[162:165] offset:16384
	s_waitcnt lgkmcnt(8)
	v_mfma_scale_f32_32x32x64_f8f6f4 v[50:65], v[246:253], v[122:129], v[50:65], v194, v194 op_sel_hi:[0,0,0]
	s_waitcnt lgkmcnt(0)
	s_barrier
	global_load_dwordx4 v[158:161], v176, s[18:19]
	global_load_dwordx4 v[162:165], v178, s[16:17]
	v_add_u32_e32 v176, 0x2000, v176
	v_add_u32_e32 v178, 0x20000, v178
	s_waitcnt lgkmcnt(4)
	v_mfma_scale_f32_32x32x64_f8f6f4 v[34:49], v[246:253], v[114:121], v[34:49], v194, v194 op_sel_hi:[0,0,0]
	s_waitcnt lgkmcnt(2)
	v_mfma_scale_f32_32x32x64_f8f6f4 v[18:33], v[246:253], v[106:113], v[18:33], v194, v194 op_sel_hi:[0,0,0]
	s_waitcnt lgkmcnt(0)
	v_mfma_scale_f32_32x32x64_f8f6f4 v[2:17], v[246:253], v[98:105], v[2:17], v194, v194 op_sel_hi:[0,0,0]
	v_max_f32_e32 v0, v66, v67
	v_max3_f32 v0, v0, v68, v69
	v_max3_f32 v0, v0, v70, v71
	v_max3_f32 v0, v0, v72, v73
	v_max3_f32 v0, v0, v74, v75
	v_max3_f32 v0, v0, v76, v77
	v_max3_f32 v0, v0, v78, v79
	v_max3_f32 v0, v0, v80, v81
	v_max_f32_e32 v177, v177, v0
	v_mov_b32_e32 v0, v177
	v_mov_b32_e32 v218, 1.0
	s_nop 0
	v_permlane32_swap_b32_e32 v177, v0
	v_max_f32_e32 v177, v177, v0
	v_cmp_ge_f32_e32 vcc, s90, v177
	s_cmp_eq_u64 vcc, exec
	s_cbranch_scc0 .Lmla_s1_newmax
; __device__ __forceinline__ void finishSM9(f32x16& p0, f32x16& p1, float alpha, float& l_reg, v8i32& p8) {
; #pragma unroll
;   for (int r = 0; r < 16; ++r) { p0[r] = __builtin_amdgcn_exp2f(p0[r]); p1[r] = __builtin_amdgcn_exp2f(p1[r]); }
;   float ps = 0;
; #pragma unroll
;   for (int r = 0; r < 16; ++r) ps += p0[r];
; #pragma unroll
;   for (int r = 0; r < 16; ++r) ps += p1[r];
;   { auto rr = __builtin_amdgcn_permlane32_swap(__float_as_uint(ps), __float_as_uint(ps), false, false);
;     ps = __uint_as_float(rr[0]) + __uint_as_float(rr[1]); }
;   l_reg = l_reg * alpha + ps;
; #pragma unroll
;   for (int g = 0; g < 4; ++g) {
;     int w = __builtin_amdgcn_cvt_pk_fp8_f32(p0[4 * g], p0[4 * g + 1], 0, false); p8[g] = __builtin_amdgcn_cvt_pk_fp8_f32(p0[4 * g + 2], p0[4 * g + 3], w, true);
;     int u = __builtin_amdgcn_cvt_pk_fp8_f32(p1[4 * g], p1[4 * g + 1], 0, false); p8[4 + g] = __builtin_amdgcn_cvt_pk_fp8_f32(p1[4 * g + 2], p1[4 * g + 3], u, true); }
; }
; __device__ __forceinline__ void pv8(f32x16* o, const char* Vt, const v8i32 p8, int r32, int hi) {
;   const int sw = (r32 >> 2) & 3, a0 = r32 * 64 + (((hi * 2) ^ sw) << 4), a1 = r32 * 64 + (((hi * 2 + 1) ^ sw) << 4);
; #pragma unroll
;   for (int d0 = 0; d0 < 4; ++d0) {
;     const v8i32 vf = cat8(*reinterpret_cast<const v4i32*>(Vt + d0 * 2048 + a0), *reinterpret_cast<const v4i32*>(Vt + d0 * 2048 + a1));
;     o[d0] = __builtin_amdgcn_mfma_scale_f32_32x32x64_f8f6f4(p8, vf, o[d0], 0, 0, 0, 127, 0, 127); }
; }
; __device__ __forceinline__ void qkt9(f32x16& p0, f32x16& p1, const char* Kn, const char* Kr, const v8i32* qf, const float init, int r32, int hi) {
; #pragma unroll
;   for (int r = 0; r < 16; ++r) { p0[r] = init; p1[r] = init; }
; #pragma unroll
;   for (int s = 0; s < 2; ++s) { const int c0 = s * 4 + hi * 2;
;     const v8i32 a0 = cat8(*reinterpret_cast<const v4i32*>(Kn + KN8SW(r32, c0)), *reinterpret_cast<const v4i32*>(Kn + KN8SW(r32, c0 + 1)));
;     const v8i32 a1 = cat8(*reinterpret_cast<const v4i32*>(Kn + 4096 + KN8SW(r32, c0)), *reinterpret_cast<const v4i32*>(Kn + 4096 + KN8SW(r32, c0 + 1)));
;     p0 = __builtin_amdgcn_mfma_scale_f32_32x32x64_f8f6f4(a0, qf[s], p0, 0, 0, 0, 127, 0, 124);
;     p1 = __builtin_amdgcn_mfma_scale_f32_32x32x64_f8f6f4(a1, qf[s], p1, 0, 0, 0, 127, 0, 124); }
;   { const int c0 = hi * 2;
.Lmla_s1_cont:
	ds_read_b128 v[114:117], v215 offset:16384
	ds_read_b128 v[118:121], v216 offset:16384
	ds_read_b128 v[222:225], v215 offset:20480
	ds_read_b128 v[226:229], v216 offset:20480
	v_exp_f32_e32 v0, v82
	v_exp_f32_e32 v177, v83
	v_exp_f32_e32 v179, v84
	v_exp_f32_e32 v254, v85
	v_add_f32_e32 v219, v0, v177
	v_cvt_pk_fp8_f32 v246, v0, v177
	v_add_f32_e32 v219, v179, v219
	v_add_f32_e32 v219, v254, v219
	v_cvt_pk_fp8_f32 v246, v179, v254 op_sel:[0,0,1]
	s_waitcnt lgkmcnt(2)
	v_mfma_scale_f32_32x32x64_f8f6f4 v[114:129], v[114:121], v[146:153], v[230:245], v194, v193 op_sel_hi:[0,0,0]
	v_exp_f32_e32 v0, v86
	v_exp_f32_e32 v177, v87
	v_exp_f32_e32 v179, v88
	v_exp_f32_e32 v254, v89
	v_add_f32_e32 v219, v0, v219
	v_add_f32_e32 v219, v177, v219
	v_cvt_pk_fp8_f32 v247, v0, v177
	v_add_f32_e32 v219, v179, v219
	v_add_f32_e32 v219, v254, v219
	v_cvt_pk_fp8_f32 v247, v179, v254 op_sel:[0,0,1]
	ds_read_b128 v[82:85], v213 offset:16384
	ds_read_b128 v[86:89], v214 offset:16384
	s_waitcnt lgkmcnt(2)
	v_mfma_scale_f32_32x32x64_f8f6f4 v[98:113], v[222:229], v[146:153], v[230:245], v194, v193 op_sel_hi:[0,0,0]
	ds_read_b128 v[222:225], v213 offset:20480
	ds_read_b128 v[226:229], v214 offset:20480
	v_exp_f32_e32 v0, v90
	v_exp_f32_e32 v177, v91
	v_exp_f32_e32 v179, v92
	v_exp_f32_e32 v254, v93
	v_add_f32_e32 v219, v0, v219
	v_add_f32_e32 v219, v177, v219
	v_cvt_pk_fp8_f32 v248, v0, v177
	v_add_f32_e32 v219, v179, v219
	v_add_f32_e32 v219, v254, v219
	v_cvt_pk_fp8_f32 v248, v179, v254 op_sel:[0,0,1]
	v_exp_f32_e32 v0, v94
	v_exp_f32_e32 v177, v95
	v_exp_f32_e32 v179, v96
	v_exp_f32_e32 v254, v97
	v_add_f32_e32 v219, v0, v219
	v_add_f32_e32 v219, v177, v219
	v_cvt_pk_fp8_f32 v249, v0, v177
	v_add_f32_e32 v219, v179, v219
	v_add_f32_e32 v219, v254, v219
	v_cvt_pk_fp8_f32 v249, v179, v254 op_sel:[0,0,1]
	ds_read_b128 v[90:93], v185 offset:32768
	ds_read_b128 v[94:97], v186 offset:32768
	s_waitcnt lgkmcnt(4)
	v_mfma_scale_f32_32x32x64_f8f6f4 v[114:129], v[82:89], v[138:145], v[114:129], v194, v193 op_sel_hi:[0,0,0]
	v_exp_f32_e32 v0, v66
	v_exp_f32_e32 v177, v67
	v_exp_f32_e32 v179, v68
	v_exp_f32_e32 v254, v69
	v_add_f32_e32 v219, v0, v219
	v_add_f32_e32 v219, v177, v219
	v_cvt_pk_fp8_f32 v250, v0, v177
	v_add_f32_e32 v219, v179, v219
	v_add_f32_e32 v219, v254, v219
	v_cvt_pk_fp8_f32 v250, v179, v254 op_sel:[0,0,1]
	s_waitcnt lgkmcnt(2)
	v_mfma_scale_f32_32x32x64_f8f6f4 v[98:113], v[222:229], v[138:145], v[98:113], v194, v193 op_sel_hi:[0,0,0]
	ds_read_b128 v[222:225], v185 offset:34816
	ds_read_b128 v[226:229], v186 offset:34816
	v_exp_f32_e32 v0, v70
	v_exp_f32_e32 v177, v71
	v_exp_f32_e32 v179, v72
	v_exp_f32_e32 v254, v73
	v_add_f32_e32 v219, v0, v219
	v_add_f32_e32 v219, v177, v219
	v_cvt_pk_fp8_f32 v251, v0, v177
	v_add_f32_e32 v219, v179, v219
	v_add_f32_e32 v219, v254, v219
	v_cvt_pk_fp8_f32 v251, v179, v254 op_sel:[0,0,1]
	v_exp_f32_e32 v0, v74
	v_exp_f32_e32 v177, v75
	v_exp_f32_e32 v179, v76
	v_exp_f32_e32 v254, v77
	v_add_f32_e32 v219, v0, v219
	v_add_f32_e32 v219, v177, v219
	v_cvt_pk_fp8_f32 v252, v0, v177
	v_add_f32_e32 v219, v179, v219
	v_add_f32_e32 v219, v254, v219
	v_cvt_pk_fp8_f32 v252, v179, v254 op_sel:[0,0,1]
	s_waitcnt lgkmcnt(2)
	v_mfma_scale_f32_32x32x64_f8f6f4 v[114:129], v[90:97], v[130:137], v[114:129], v194, v193 op_sel_hi:[0,0,0]
	v_exp_f32_e32 v0, v78
	v_exp_f32_e32 v177, v79
	v_exp_f32_e32 v179, v80
	v_exp_f32_e32 v254, v81
	v_add_f32_e32 v219, v0, v219
	v_add_f32_e32 v219, v177, v219
	v_cvt_pk_fp8_f32 v253, v0, v177
	v_add_f32_e32 v219, v179, v219
	v_add_f32_e32 v219, v254, v219
	v_cvt_pk_fp8_f32 v253, v179, v254 op_sel:[0,0,1]
	ds_read_b128 v[90:93], v185 offset:43008
	ds_read_b128 v[94:97], v186 offset:43008
	ds_read_b128 v[82:85], v185 offset:45056
	ds_read_b128 v[86:89], v186 offset:45056
	ds_read_b128 v[74:77], v185 offset:47104
	ds_read_b128 v[78:81], v186 offset:47104
	ds_read_b128 v[66:69], v185 offset:49152
	ds_read_b128 v[70:73], v186 offset:49152
	s_waitcnt lgkmcnt(8)
	v_mfma_scale_f32_32x32x64_f8f6f4 v[98:113], v[222:229], v[130:137], v[98:113], v194, v193 op_sel_hi:[0,0,0]
	v_mov_b32_e32 v0, v219
	s_nop 1
	v_permlane32_swap_b32_e32 v219, v0
	v_add_f32_e32 v219, v219, v0
	v_fma_f32 v209, v209, v218, v219
	v_max_f32_e32 v177, v114, v115
	v_max3_f32 v177, v177, v116, v117
	v_max3_f32 v177, v177, v118, v119
	v_max3_f32 v177, v177, v120, v121
	v_max3_f32 v177, v177, v122, v123
	v_max3_f32 v177, v177, v124, v125
	v_max3_f32 v177, v177, v126, v127
	v_max3_f32 v177, v177, v128, v129
	s_waitcnt vmcnt(0)
	ds_write_b128 v210, v[158:161] offset:8192
	ds_write_b128 v211, v[162:165] offset:24576
	s_waitcnt lgkmcnt(8)
	v_mfma_scale_f32_32x32x64_f8f6f4 v[50:65], v[246:253], v[90:97], v[50:65], v194, v194 op_sel_hi:[0,0,0]
	s_waitcnt lgkmcnt(0)
	s_barrier
	global_load_dwordx4 v[158:161], v176, s[18:19]
	global_load_dwordx4 v[162:165], v178, s[16:17]
	v_add_u32_e32 v176, 0x2000, v176
	v_add_u32_e32 v178, 0x20000, v178
	s_waitcnt lgkmcnt(4)
	v_mfma_scale_f32_32x32x64_f8f6f4 v[34:49], v[246:253], v[82:89], v[34:49], v194, v194 op_sel_hi:[0,0,0]
	s_waitcnt lgkmcnt(2)
	v_mfma_scale_f32_32x32x64_f8f6f4 v[18:33], v[246:253], v[74:81], v[18:33], v194, v194 op_sel_hi:[0,0,0]
	s_waitcnt lgkmcnt(0)
	v_mfma_scale_f32_32x32x64_f8f6f4 v[2:17], v[246:253], v[66:73], v[2:17], v194, v194 op_sel_hi:[0,0,0]
	v_max_f32_e32 v0, v98, v99
	v_max3_f32 v0, v0, v100, v101
	v_max3_f32 v0, v0, v102, v103
	v_max3_f32 v0, v0, v104, v105
	v_max3_f32 v0, v0, v106, v107
	v_max3_f32 v0, v0, v108, v109
	v_max3_f32 v0, v0, v110, v111
	v_max3_f32 v0, v0, v112, v113
	v_max_f32_e32 v177, v177, v0
	v_mov_b32_e32 v0, v177
	v_mov_b32_e32 v221, 1.0
	s_nop 0
	v_permlane32_swap_b32_e32 v177, v0
	v_max_f32_e32 v177, v177, v0
	v_cmp_ge_f32_e32 vcc, s90, v177
	s_cmp_eq_u64 vcc, exec
	s_cbranch_scc0 .Lmla_s2_newmax
; __device__ __forceinline__ void finishSM9(f32x16& p0, f32x16& p1, float alpha, float& l_reg, v8i32& p8) {
; #pragma unroll
;   for (int r = 0; r < 16; ++r) { p0[r] = __builtin_amdgcn_exp2f(p0[r]); p1[r] = __builtin_amdgcn_exp2f(p1[r]); }
;   float ps = 0;
; #pragma unroll
;   for (int r = 0; r < 16; ++r) ps += p0[r];
; #pragma unroll
;   for (int r = 0; r < 16; ++r) ps += p1[r];
;   { auto rr = __builtin_amdgcn_permlane32_swap(__float_as_uint(ps), __float_as_uint(ps), false, false);
;     ps = __uint_as_float(rr[0]) + __uint_as_float(rr[1]); }
;   l_reg = l_reg * alpha + ps;
; #pragma unroll
;   for (int g = 0; g < 4; ++g) {
;     int w = __builtin_amdgcn_cvt_pk_fp8_f32(p0[4 * g], p0[4 * g + 1], 0, false); p8[g] = __builtin_amdgcn_cvt_pk_fp8_f32(p0[4 * g + 2], p0[4 * g + 3], w, true);
;     int u = __builtin_amdgcn_cvt_pk_fp8_f32(p1[4 * g], p1[4 * g + 1], 0, false); p8[4 + g] = __builtin_amdgcn_cvt_pk_fp8_f32(p1[4 * g + 2], p1[4 * g + 3], u, true); }
; }
; __device__ __forceinline__ void pv8(f32x16* o, const char* Vt, const v8i32 p8, int r32, int hi) {
;   const int sw = (r32 >> 2) & 3, a0 = r32 * 64 + (((hi * 2) ^ sw) << 4), a1 = r32 * 64 + (((hi * 2 + 1) ^ sw) << 4);
; #pragma unroll
;   for (int d0 = 0; d0 < 4; ++d0) {
;     const v8i32 vf = cat8(*reinterpret_cast<const v4i32*>(Vt + d0 * 2048 + a0), *reinterpret_cast<const v4i32*>(Vt + d0 * 2048 + a1));
;     o[d0] = __builtin_amdgcn_mfma_scale_f32_32x32x64_f8f6f4(p8, vf, o[d0], 0, 0, 0, 127, 0, 127); }
; }
; __device__ __forceinline__ void qkt9(f32x16& p0, f32x16& p1, const char* Kn, const char* Kr, const v8i32* qf, const float init, int r32, int hi) {
; #pragma unroll
;   for (int r = 0; r < 16; ++r) { p0[r] = init; p1[r] = init; }
; #pragma unroll
;   for (int s = 0; s < 2; ++s) { const int c0 = s * 4 + hi * 2;
;     const v8i32 a0 = cat8(*reinterpret_cast<const v4i32*>(Kn + KN8SW(r32, c0)), *reinterpret_cast<const v4i32*>(Kn + KN8SW(r32, c0 + 1)));
;     const v8i32 a1 = cat8(*reinterpret_cast<const v4i32*>(Kn + 4096 + KN8SW(r32, c0)), *reinterpret_cast<const v4i32*>(Kn + 4096 + KN8SW(r32, c0 + 1)));
;     p0 = __builtin_amdgcn_mfma_scale_f32_32x32x64_f8f6f4(a0, qf[s], p0, 0, 0, 0, 127, 0, 124);
;     p1 = __builtin_amdgcn_mfma_scale_f32_32x32x64_f8f6f4(a1, qf[s], p1, 0, 0, 0, 127, 0, 124); }
;   { const int c0 = hi * 2;
.Lmla_s2_cont:
	ds_read_b128 v[82:85], v215 offset:24576
	ds_read_b128 v[86:89], v216 offset:24576
	ds_read_b128 v[222:225], v215 offset:28672
	ds_read_b128 v[226:229], v216 offset:28672
	v_exp_f32_e32 v0, v114
	v_exp_f32_e32 v177, v115
	v_exp_f32_e32 v179, v116
	v_exp_f32_e32 v254, v117
	v_add_f32_e32 v219, v0, v177
	v_cvt_pk_fp8_f32 v246, v0, v177
	v_add_f32_e32 v219, v179, v219
	v_add_f32_e32 v219, v254, v219
	v_cvt_pk_fp8_f32 v246, v179, v254 op_sel:[0,0,1]
	s_waitcnt lgkmcnt(2)
	v_mfma_scale_f32_32x32x64_f8f6f4 v[82:97], v[82:89], v[146:153], v[230:245], v194, v193 op_sel_hi:[0,0,0]
	v_exp_f32_e32 v0, v118
	v_exp_f32_e32 v177, v119
	v_exp_f32_e32 v179, v120
	v_exp_f32_e32 v254, v121
	v_add_f32_e32 v219, v0, v219
	v_add_f32_e32 v219, v177, v219
	v_cvt_pk_fp8_f32 v247, v0, v177
	v_add_f32_e32 v219, v179, v219
	v_add_f32_e32 v219, v254, v219
	v_cvt_pk_fp8_f32 v247, v179, v254 op_sel:[0,0,1]
	ds_read_b128 v[114:117], v213 offset:24576
	ds_read_b128 v[118:121], v214 offset:24576
	s_waitcnt lgkmcnt(2)
	v_mfma_scale_f32_32x32x64_f8f6f4 v[66:81], v[222:229], v[146:153], v[230:245], v194, v193 op_sel_hi:[0,0,0]
	ds_read_b128 v[222:225], v213 offset:28672
	ds_read_b128 v[226:229], v214 offset:28672
	v_exp_f32_e32 v0, v122
	v_exp_f32_e32 v177, v123
	v_exp_f32_e32 v179, v124
	v_exp_f32_e32 v254, v125
	v_add_f32_e32 v219, v0, v219
	v_add_f32_e32 v219, v177, v219
	v_cvt_pk_fp8_f32 v248, v0, v177
	v_add_f32_e32 v219, v179, v219
	v_add_f32_e32 v219, v254, v219
	v_cvt_pk_fp8_f32 v248, v179, v254 op_sel:[0,0,1]
	v_exp_f32_e32 v0, v126
	v_exp_f32_e32 v177, v127
	v_exp_f32_e32 v179, v128
	v_exp_f32_e32 v254, v129
	v_add_f32_e32 v219, v0, v219
	v_add_f32_e32 v219, v177, v219
	v_cvt_pk_fp8_f32 v249, v0, v177
	v_add_f32_e32 v219, v179, v219
	v_add_f32_e32 v219, v254, v219
	v_cvt_pk_fp8_f32 v249, v179, v254 op_sel:[0,0,1]
	ds_read_b128 v[122:125], v185 offset:36864
	ds_read_b128 v[126:129], v186 offset:36864
	s_waitcnt lgkmcnt(4)
	v_mfma_scale_f32_32x32x64_f8f6f4 v[82:97], v[114:121], v[138:145], v[82:97], v194, v193 op_sel_hi:[0,0,0]
	v_exp_f32_e32 v0, v98
	v_exp_f32_e32 v177, v99
	v_exp_f32_e32 v179, v100
	v_exp_f32_e32 v254, v101
	v_add_f32_e32 v219, v0, v219
	v_add_f32_e32 v219, v177, v219
	v_cvt_pk_fp8_f32 v250, v0, v177
	v_add_f32_e32 v219, v179, v219
	v_add_f32_e32 v219, v254, v219
	v_cvt_pk_fp8_f32 v250, v179, v254 op_sel:[0,0,1]
	s_waitcnt lgkmcnt(2)
	v_mfma_scale_f32_32x32x64_f8f6f4 v[66:81], v[222:229], v[138:145], v[66:81], v194, v193 op_sel_hi:[0,0,0]
	ds_read_b128 v[222:225], v185 offset:38912
	ds_read_b128 v[226:229], v186 offset:38912
	v_exp_f32_e32 v0, v102
	v_exp_f32_e32 v177, v103
	v_exp_f32_e32 v179, v104
	v_exp_f32_e32 v254, v105
	v_add_f32_e32 v219, v0, v219
	v_add_f32_e32 v219, v177, v219
	v_cvt_pk_fp8_f32 v251, v0, v177
	v_add_f32_e32 v219, v179, v219
	v_add_f32_e32 v219, v254, v219
	v_cvt_pk_fp8_f32 v251, v179, v254 op_sel:[0,0,1]
	v_exp_f32_e32 v0, v106
	v_exp_f32_e32 v177, v107
	v_exp_f32_e32 v179, v108
	v_exp_f32_e32 v254, v109
	v_add_f32_e32 v219, v0, v219
	v_add_f32_e32 v219, v177, v219
	v_cvt_pk_fp8_f32 v252, v0, v177
	v_add_f32_e32 v219, v179, v219
	v_add_f32_e32 v219, v254, v219
	v_cvt_pk_fp8_f32 v252, v179, v254 op_sel:[0,0,1]
	s_waitcnt lgkmcnt(2)
	v_mfma_scale_f32_32x32x64_f8f6f4 v[82:97], v[122:129], v[130:137], v[82:97], v194, v193 op_sel_hi:[0,0,0]
	v_exp_f32_e32 v0, v110
	v_exp_f32_e32 v177, v111
	v_exp_f32_e32 v179, v112
	v_exp_f32_e32 v254, v113
	v_add_f32_e32 v219, v0, v219
	v_add_f32_e32 v219, v177, v219
	v_cvt_pk_fp8_f32 v253, v0, v177
	v_add_f32_e32 v219, v179, v219
	v_add_f32_e32 v219, v254, v219
	v_cvt_pk_fp8_f32 v253, v179, v254 op_sel:[0,0,1]
	ds_read_b128 v[122:125], v185 offset:0
	ds_read_b128 v[126:129], v186 offset:0
	ds_read_b128 v[114:117], v185 offset:2048
	ds_read_b128 v[118:121], v186 offset:2048
	ds_read_b128 v[106:109], v185 offset:4096
	ds_read_b128 v[110:113], v186 offset:4096
	ds_read_b128 v[98:101], v185 offset:6144
	ds_read_b128 v[102:105], v186 offset:6144
	s_waitcnt lgkmcnt(8)
	v_mfma_scale_f32_32x32x64_f8f6f4 v[66:81], v[222:229], v[130:137], v[66:81], v194, v193 op_sel_hi:[0,0,0]
	v_mov_b32_e32 v0, v219
	s_nop 1
	v_permlane32_swap_b32_e32 v219, v0
	v_add_f32_e32 v219, v219, v0
	v_fma_f32 v209, v209, v221, v219
	v_max_f32_e32 v177, v82, v83
	v_max3_f32 v177, v177, v84, v85
	v_max3_f32 v177, v177, v86, v87
	v_max3_f32 v177, v177, v88, v89
	v_max3_f32 v177, v177, v90, v91
	v_max3_f32 v177, v177, v92, v93
	v_max3_f32 v177, v177, v94, v95
	v_max3_f32 v177, v177, v96, v97
	s_waitcnt vmcnt(0)
	ds_write_b128 v210, v[158:161] offset:43008
	ds_write_b128 v211, v[162:165] offset:51200
	s_waitcnt lgkmcnt(8)
	v_mfma_scale_f32_32x32x64_f8f6f4 v[50:65], v[246:253], v[122:129], v[50:65], v194, v194 op_sel_hi:[0,0,0]
	s_waitcnt lgkmcnt(0)
	s_barrier
	global_load_dwordx4 v[158:161], v176, s[18:19]
	global_load_dwordx4 v[162:165], v178, s[16:17]
	v_add_u32_e32 v176, 0x2000, v176
	v_add_u32_e32 v178, 0x20000, v178
	s_waitcnt lgkmcnt(4)
	v_mfma_scale_f32_32x32x64_f8f6f4 v[34:49], v[246:253], v[114:121], v[34:49], v194, v194 op_sel_hi:[0,0,0]
	s_waitcnt lgkmcnt(2)
	v_mfma_scale_f32_32x32x64_f8f6f4 v[18:33], v[246:253], v[106:113], v[18:33], v194, v194 op_sel_hi:[0,0,0]
	s_waitcnt lgkmcnt(0)
	v_mfma_scale_f32_32x32x64_f8f6f4 v[2:17], v[246:253], v[98:105], v[2:17], v194, v194 op_sel_hi:[0,0,0]
	v_max_f32_e32 v0, v66, v67
	v_max3_f32 v0, v0, v68, v69
	v_max3_f32 v0, v0, v70, v71
	v_max3_f32 v0, v0, v72, v73
	v_max3_f32 v0, v0, v74, v75
	v_max3_f32 v0, v0, v76, v77
	v_max3_f32 v0, v0, v78, v79
	v_max3_f32 v0, v0, v80, v81
	v_max_f32_e32 v177, v177, v0
	v_mov_b32_e32 v0, v177
	v_mov_b32_e32 v218, 1.0
	s_nop 0
	v_permlane32_swap_b32_e32 v177, v0
	v_max_f32_e32 v177, v177, v0
	v_cmp_ge_f32_e32 vcc, s90, v177
	s_cmp_eq_u64 vcc, exec
	s_cbranch_scc0 .Lmla_s3_newmax
; __device__ __forceinline__ void finishSM9(f32x16& p0, f32x16& p1, float alpha, float& l_reg, v8i32& p8) {
; #pragma unroll
;   for (int r = 0; r < 16; ++r) { p0[r] = __builtin_amdgcn_exp2f(p0[r]); p1[r] = __builtin_amdgcn_exp2f(p1[r]); }
;   float ps = 0;
; #pragma unroll
;   for (int r = 0; r < 16; ++r) ps += p0[r];
; #pragma unroll
;   for (int r = 0; r < 16; ++r) ps += p1[r];
;   { auto rr = __builtin_amdgcn_permlane32_swap(__float_as_uint(ps), __float_as_uint(ps), false, false);
;     ps = __uint_as_float(rr[0]) + __uint_as_float(rr[1]); }
;   l_reg = l_reg * alpha + ps;
; #pragma unroll
;   for (int g = 0; g < 4; ++g) {
;     int w = __builtin_amdgcn_cvt_pk_fp8_f32(p0[4 * g], p0[4 * g + 1], 0, false); p8[g] = __builtin_amdgcn_cvt_pk_fp8_f32(p0[4 * g + 2], p0[4 * g + 3], w, true);
;     int u = __builtin_amdgcn_cvt_pk_fp8_f32(p1[4 * g], p1[4 * g + 1], 0, false); p8[4 + g] = __builtin_amdgcn_cvt_pk_fp8_f32(p1[4 * g + 2], p1[4 * g + 3], u, true); }
; }
; __device__ __forceinline__ void pv8(f32x16* o, const char* Vt, const v8i32 p8, int r32, int hi) {
;   const int sw = (r32 >> 2) & 3, a0 = r32 * 64 + (((hi * 2) ^ sw) << 4), a1 = r32 * 64 + (((hi * 2 + 1) ^ sw) << 4);
; #pragma unroll
;   for (int d0 = 0; d0 < 4; ++d0) {
;     const v8i32 vf = cat8(*reinterpret_cast<const v4i32*>(Vt + d0 * 2048 + a0), *reinterpret_cast<const v4i32*>(Vt + d0 * 2048 + a1));
;     o[d0] = __builtin_amdgcn_mfma_scale_f32_32x32x64_f8f6f4(p8, vf, o[d0], 0, 0, 0, 127, 0, 127); }
; }
; __device__ __forceinline__ void qkt9(f32x16& p0, f32x16& p1, const char* Kn, const char* Kr, const v8i32* qf, const float init, int r32, int hi) {
; #pragma unroll
;   for (int r = 0; r < 16; ++r) { p0[r] = init; p1[r] = init; }
; #pragma unroll
;   for (int s = 0; s < 2; ++s) { const int c0 = s * 4 + hi * 2;
;     const v8i32 a0 = cat8(*reinterpret_cast<const v4i32*>(Kn + KN8SW(r32, c0)), *reinterpret_cast<const v4i32*>(Kn + KN8SW(r32, c0 + 1)));
;     const v8i32 a1 = cat8(*reinterpret_cast<const v4i32*>(Kn + 4096 + KN8SW(r32, c0)), *reinterpret_cast<const v4i32*>(Kn + 4096 + KN8SW(r32, c0 + 1)));
;     p0 = __builtin_amdgcn_mfma_scale_f32_32x32x64_f8f6f4(a0, qf[s], p0, 0, 0, 0, 127, 0, 124);
;     p1 = __builtin_amdgcn_mfma_scale_f32_32x32x64_f8f6f4(a1, qf[s], p1, 0, 0, 0, 127, 0, 124); }
;   { const int c0 = hi * 2;
.Lmla_s3_cont:
	ds_read_b128 v[114:117], v215 offset:51200
	ds_read_b128 v[118:121], v216 offset:51200
	ds_read_b128 v[222:225], v215 offset:55296
	ds_read_b128 v[226:229], v216 offset:55296
	v_exp_f32_e32 v0, v82
	v_exp_f32_e32 v177, v83
	v_exp_f32_e32 v179, v84
	v_exp_f32_e32 v254, v85
	v_add_f32_e32 v219, v0, v177
	v_cvt_pk_fp8_f32 v246, v0, v177
	v_add_f32_e32 v219, v179, v219
	v_add_f32_e32 v219, v254, v219
	v_cvt_pk_fp8_f32 v246, v179, v254 op_sel:[0,0,1]
	s_waitcnt lgkmcnt(2)
	v_mfma_scale_f32_32x32x64_f8f6f4 v[114:129], v[114:121], v[146:153], v[230:245], v194, v193 op_sel_hi:[0,0,0]
	v_exp_f32_e32 v0, v86
	v_exp_f32_e32 v177, v87
	v_exp_f32_e32 v179, v88
	v_exp_f32_e32 v254, v89
	v_add_f32_e32 v219, v0, v219
	v_add_f32_e32 v219, v177, v219
	v_cvt_pk_fp8_f32 v247, v0, v177
	v_add_f32_e32 v219, v179, v219
	v_add_f32_e32 v219, v254, v219
	v_cvt_pk_fp8_f32 v247, v179, v254 op_sel:[0,0,1]
	ds_read_b128 v[82:85], v213 offset:51200
	ds_read_b128 v[86:89], v214 offset:51200
	s_waitcnt lgkmcnt(2)
	v_mfma_scale_f32_32x32x64_f8f6f4 v[98:113], v[222:229], v[146:153], v[230:245], v194, v193 op_sel_hi:[0,0,0]
	ds_read_b128 v[222:225], v213 offset:55296
	ds_read_b128 v[226:229], v214 offset:55296
	v_exp_f32_e32 v0, v90
	v_exp_f32_e32 v177, v91
	v_exp_f32_e32 v179, v92
	v_exp_f32_e32 v254, v93
	v_add_f32_e32 v219, v0, v219
	v_add_f32_e32 v219, v177, v219
	v_cvt_pk_fp8_f32 v248, v0, v177
	v_add_f32_e32 v219, v179, v219
	v_add_f32_e32 v219, v254, v219
	v_cvt_pk_fp8_f32 v248, v179, v254 op_sel:[0,0,1]
	v_exp_f32_e32 v0, v94
	v_exp_f32_e32 v177, v95
	v_exp_f32_e32 v179, v96
	v_exp_f32_e32 v254, v97
	v_add_f32_e32 v219, v0, v219
	v_add_f32_e32 v219, v177, v219
	v_cvt_pk_fp8_f32 v249, v0, v177
	v_add_f32_e32 v219, v179, v219
	v_add_f32_e32 v219, v254, v219
	v_cvt_pk_fp8_f32 v249, v179, v254 op_sel:[0,0,1]
	ds_read_b128 v[90:93], v185 offset:59392
	ds_read_b128 v[94:97], v186 offset:59392
	s_waitcnt lgkmcnt(4)
	v_mfma_scale_f32_32x32x64_f8f6f4 v[114:129], v[82:89], v[138:145], v[114:129], v194, v193 op_sel_hi:[0,0,0]
	v_exp_f32_e32 v0, v66
	v_exp_f32_e32 v177, v67
	v_exp_f32_e32 v179, v68
	v_exp_f32_e32 v254, v69
	v_add_f32_e32 v219, v0, v219
	v_add_f32_e32 v219, v177, v219
	v_cvt_pk_fp8_f32 v250, v0, v177
	v_add_f32_e32 v219, v179, v219
	v_add_f32_e32 v219, v254, v219
	v_cvt_pk_fp8_f32 v250, v179, v254 op_sel:[0,0,1]
	s_waitcnt lgkmcnt(2)
	v_mfma_scale_f32_32x32x64_f8f6f4 v[98:113], v[222:229], v[138:145], v[98:113], v194, v193 op_sel_hi:[0,0,0]
	ds_read_b128 v[222:225], v185 offset:61440
	ds_read_b128 v[226:229], v186 offset:61440
	v_exp_f32_e32 v0, v70
	v_exp_f32_e32 v177, v71
	v_exp_f32_e32 v179, v72
	v_exp_f32_e32 v254, v73
	v_add_f32_e32 v219, v0, v219
	v_add_f32_e32 v219, v177, v219
	v_cvt_pk_fp8_f32 v251, v0, v177
	v_add_f32_e32 v219, v179, v219
	v_add_f32_e32 v219, v254, v219
	v_cvt_pk_fp8_f32 v251, v179, v254 op_sel:[0,0,1]
	v_exp_f32_e32 v0, v74
	v_exp_f32_e32 v177, v75
	v_exp_f32_e32 v179, v76
	v_exp_f32_e32 v254, v77
	v_add_f32_e32 v219, v0, v219
	v_add_f32_e32 v219, v177, v219
	v_cvt_pk_fp8_f32 v252, v0, v177
	v_add_f32_e32 v219, v179, v219
	v_add_f32_e32 v219, v254, v219
	v_cvt_pk_fp8_f32 v252, v179, v254 op_sel:[0,0,1]
	s_waitcnt lgkmcnt(2)
	v_mfma_scale_f32_32x32x64_f8f6f4 v[114:129], v[90:97], v[130:137], v[114:129], v194, v193 op_sel_hi:[0,0,0]
	v_exp_f32_e32 v0, v78
	v_exp_f32_e32 v177, v79
	v_exp_f32_e32 v179, v80
	v_exp_f32_e32 v254, v81
	v_add_f32_e32 v219, v0, v219
	v_add_f32_e32 v219, v177, v219
	v_cvt_pk_fp8_f32 v253, v0, v177
	v_add_f32_e32 v219, v179, v219
	v_add_f32_e32 v219, v254, v219
	v_cvt_pk_fp8_f32 v253, v179, v254 op_sel:[0,0,1]
	ds_read_b128 v[90:93], v185 offset:8192
	ds_read_b128 v[94:97], v186 offset:8192
	ds_read_b128 v[82:85], v185 offset:10240
	ds_read_b128 v[86:89], v186 offset:10240
	ds_read_b128 v[74:77], v185 offset:12288
	ds_read_b128 v[78:81], v186 offset:12288
	ds_read_b128 v[66:69], v185 offset:14336
	ds_read_b128 v[70:73], v186 offset:14336
	s_waitcnt lgkmcnt(8)
	v_mfma_scale_f32_32x32x64_f8f6f4 v[98:113], v[222:229], v[130:137], v[98:113], v194, v193 op_sel_hi:[0,0,0]
	v_mov_b32_e32 v0, v219
	s_nop 1
	v_permlane32_swap_b32_e32 v219, v0
	v_add_f32_e32 v219, v219, v0
	v_fma_f32 v209, v209, v218, v219
	v_max_f32_e32 v177, v114, v115
	v_max3_f32 v177, v177, v116, v117
	v_max3_f32 v177, v177, v118, v119
	v_max3_f32 v177, v177, v120, v121
	v_max3_f32 v177, v177, v122, v123
	v_max3_f32 v177, v177, v124, v125
	v_max3_f32 v177, v177, v126, v127
	v_max3_f32 v177, v177, v128, v129
	s_waitcnt vmcnt(0)
	ds_write_b128 v210, v[158:161]
	ds_write_b128 v211, v[162:165] offset:16384
	s_waitcnt lgkmcnt(8)
	v_mfma_scale_f32_32x32x64_f8f6f4 v[50:65], v[246:253], v[90:97], v[50:65], v194, v194 op_sel_hi:[0,0,0]
	s_waitcnt lgkmcnt(0)
	s_barrier
	global_load_dwordx4 v[158:161], v176, s[18:19]
	global_load_dwordx4 v[162:165], v178, s[16:17]
	v_add_u32_e32 v176, 0x2000, v176
	v_add_u32_e32 v178, 0x20000, v178
	s_waitcnt lgkmcnt(4)
	v_mfma_scale_f32_32x32x64_f8f6f4 v[34:49], v[246:253], v[82:89], v[34:49], v194, v194 op_sel_hi:[0,0,0]
	s_waitcnt lgkmcnt(2)
	v_mfma_scale_f32_32x32x64_f8f6f4 v[18:33], v[246:253], v[74:81], v[18:33], v194, v194 op_sel_hi:[0,0,0]
	s_waitcnt lgkmcnt(0)
	v_mfma_scale_f32_32x32x64_f8f6f4 v[2:17], v[246:253], v[66:73], v[2:17], v194, v194 op_sel_hi:[0,0,0]
	v_max_f32_e32 v0, v98, v99
	v_max3_f32 v0, v0, v100, v101
	v_max3_f32 v0, v0, v102, v103
	v_max3_f32 v0, v0, v104, v105
	v_max3_f32 v0, v0, v106, v107
	v_max3_f32 v0, v0, v108, v109
	v_max3_f32 v0, v0, v110, v111
	v_max3_f32 v0, v0, v112, v113
	v_max_f32_e32 v177, v177, v0
	v_mov_b32_e32 v0, v177
	v_mov_b32_e32 v221, 1.0
	s_nop 0
	v_permlane32_swap_b32_e32 v177, v0
	v_max_f32_e32 v177, v177, v0
	v_cmp_ge_f32_e32 vcc, s90, v177
	s_cmp_eq_u64 vcc, exec
	s_cbranch_scc0 .Lmla_s4_newmax
; __device__ __forceinline__ void finishSM9(f32x16& p0, f32x16& p1, float alpha, float& l_reg, v8i32& p8) {
; #pragma unroll
;   for (int r = 0; r < 16; ++r) { p0[r] = __builtin_amdgcn_exp2f(p0[r]); p1[r] = __builtin_amdgcn_exp2f(p1[r]); }
;   float ps = 0;
; #pragma unroll
;   for (int r = 0; r < 16; ++r) ps += p0[r];
; #pragma unroll
;   for (int r = 0; r < 16; ++r) ps += p1[r];
;   { auto rr = __builtin_amdgcn_permlane32_swap(__float_as_uint(ps), __float_as_uint(ps), false, false);
;     ps = __uint_as_float(rr[0]) + __uint_as_float(rr[1]); }
;   l_reg = l_reg * alpha + ps;
; #pragma unroll
;   for (int g = 0; g < 4; ++g) {
;     int w = __builtin_amdgcn_cvt_pk_fp8_f32(p0[4 * g], p0[4 * g + 1], 0, false); p8[g] = __builtin_amdgcn_cvt_pk_fp8_f32(p0[4 * g + 2], p0[4 * g + 3], w, true);
;     int u = __builtin_amdgcn_cvt_pk_fp8_f32(p1[4 * g], p1[4 * g + 1], 0, false); p8[4 + g] = __builtin_amdgcn_cvt_pk_fp8_f32(p1[4 * g + 2], p1[4 * g + 3], u, true); }
; }
; __device__ __forceinline__ void pv8(f32x16* o, const char* Vt, const v8i32 p8, int r32, int hi) {
;   const int sw = (r32 >> 2) & 3, a0 = r32 * 64 + (((hi * 2) ^ sw) << 4), a1 = r32 * 64 + (((hi * 2 + 1) ^ sw) << 4);
; #pragma unroll
;   for (int d0 = 0; d0 < 4; ++d0) {
;     const v8i32 vf = cat8(*reinterpret_cast<const v4i32*>(Vt + d0 * 2048 + a0), *reinterpret_cast<const v4i32*>(Vt + d0 * 2048 + a1));
;     o[d0] = __builtin_amdgcn_mfma_scale_f32_32x32x64_f8f6f4(p8, vf, o[d0], 0, 0, 0, 127, 0, 127); }
; }
; __device__ __forceinline__ void qkt9(f32x16& p0, f32x16& p1, const char* Kn, const char* Kr, const v8i32* qf, const float init, int r32, int hi) {
; #pragma unroll
;   for (int r = 0; r < 16; ++r) { p0[r] = init; p1[r] = init; }
; #pragma unroll
;   for (int s = 0; s < 2; ++s) { const int c0 = s * 4 + hi * 2;
;     const v8i32 a0 = cat8(*reinterpret_cast<const v4i32*>(Kn + KN8SW(r32, c0)), *reinterpret_cast<const v4i32*>(Kn + KN8SW(r32, c0 + 1)));
;     const v8i32 a1 = cat8(*reinterpret_cast<const v4i32*>(Kn + 4096 + KN8SW(r32, c0)), *reinterpret_cast<const v4i32*>(Kn + 4096 + KN8SW(r32, c0 + 1)));
;     p0 = __builtin_amdgcn_mfma_scale_f32_32x32x64_f8f6f4(a0, qf[s], p0, 0, 0, 0, 127, 0, 124);
;     p1 = __builtin_amdgcn_mfma_scale_f32_32x32x64_f8f6f4(a1, qf[s], p1, 0, 0, 0, 127, 0, 124); }
;   { const int c0 = hi * 2;
.Lmla_s4_cont:
	ds_read_b128 v[82:85], v215 offset:16384
	ds_read_b128 v[86:89], v216 offset:16384
	ds_read_b128 v[222:225], v215 offset:20480
	ds_read_b128 v[226:229], v216 offset:20480
	v_exp_f32_e32 v0, v114
	v_exp_f32_e32 v177, v115
	v_exp_f32_e32 v179, v116
	v_exp_f32_e32 v254, v117
	v_add_f32_e32 v219, v0, v177
	v_cvt_pk_fp8_f32 v246, v0, v177
	v_add_f32_e32 v219, v179, v219
	v_add_f32_e32 v219, v254, v219
	v_cvt_pk_fp8_f32 v246, v179, v254 op_sel:[0,0,1]
	s_waitcnt lgkmcnt(2)
	v_mfma_scale_f32_32x32x64_f8f6f4 v[82:97], v[82:89], v[146:153], v[230:245], v194, v193 op_sel_hi:[0,0,0]
	v_exp_f32_e32 v0, v118
	v_exp_f32_e32 v177, v119
	v_exp_f32_e32 v179, v120
	v_exp_f32_e32 v254, v121
	v_add_f32_e32 v219, v0, v219
	v_add_f32_e32 v219, v177, v219
	v_cvt_pk_fp8_f32 v247, v0, v177
	v_add_f32_e32 v219, v179, v219
	v_add_f32_e32 v219, v254, v219
	v_cvt_pk_fp8_f32 v247, v179, v254 op_sel:[0,0,1]
	ds_read_b128 v[114:117], v213 offset:16384
	ds_read_b128 v[118:121], v214 offset:16384
	s_waitcnt lgkmcnt(2)
	v_mfma_scale_f32_32x32x64_f8f6f4 v[66:81], v[222:229], v[146:153], v[230:245], v194, v193 op_sel_hi:[0,0,0]
	ds_read_b128 v[222:225], v213 offset:20480
	ds_read_b128 v[226:229], v214 offset:20480
	v_exp_f32_e32 v0, v122
	v_exp_f32_e32 v177, v123
	v_exp_f32_e32 v179, v124
	v_exp_f32_e32 v254, v125
	v_add_f32_e32 v219, v0, v219
	v_add_f32_e32 v219, v177, v219
	v_cvt_pk_fp8_f32 v248, v0, v177
	v_add_f32_e32 v219, v179, v219
	v_add_f32_e32 v219, v254, v219
	v_cvt_pk_fp8_f32 v248, v179, v254 op_sel:[0,0,1]
	v_exp_f32_e32 v0, v126
	v_exp_f32_e32 v177, v127
	v_exp_f32_e32 v179, v128
	v_exp_f32_e32 v254, v129
	v_add_f32_e32 v219, v0, v219
	v_add_f32_e32 v219, v177, v219
	v_cvt_pk_fp8_f32 v249, v0, v177
	v_add_f32_e32 v219, v179, v219
	v_add_f32_e32 v219, v254, v219
	v_cvt_pk_fp8_f32 v249, v179, v254 op_sel:[0,0,1]
	ds_read_b128 v[122:125], v185 offset:32768
	ds_read_b128 v[126:129], v186 offset:32768
	s_waitcnt lgkmcnt(4)
	v_mfma_scale_f32_32x32x64_f8f6f4 v[82:97], v[114:121], v[138:145], v[82:97], v194, v193 op_sel_hi:[0,0,0]
	v_exp_f32_e32 v0, v98
	v_exp_f32_e32 v177, v99
	v_exp_f32_e32 v179, v100
	v_exp_f32_e32 v254, v101
	v_add_f32_e32 v219, v0, v219
	v_add_f32_e32 v219, v177, v219
	v_cvt_pk_fp8_f32 v250, v0, v177
	v_add_f32_e32 v219, v179, v219
	v_add_f32_e32 v219, v254, v219
	v_cvt_pk_fp8_f32 v250, v179, v254 op_sel:[0,0,1]
	s_waitcnt lgkmcnt(2)
	v_mfma_scale_f32_32x32x64_f8f6f4 v[66:81], v[222:229], v[138:145], v[66:81], v194, v193 op_sel_hi:[0,0,0]
	ds_read_b128 v[222:225], v185 offset:34816
	ds_read_b128 v[226:229], v186 offset:34816
	v_exp_f32_e32 v0, v102
	v_exp_f32_e32 v177, v103
	v_exp_f32_e32 v179, v104
	v_exp_f32_e32 v254, v105
	v_add_f32_e32 v219, v0, v219
	v_add_f32_e32 v219, v177, v219
	v_cvt_pk_fp8_f32 v251, v0, v177
	v_add_f32_e32 v219, v179, v219
	v_add_f32_e32 v219, v254, v219
	v_cvt_pk_fp8_f32 v251, v179, v254 op_sel:[0,0,1]
	v_exp_f32_e32 v0, v106
	v_exp_f32_e32 v177, v107
	v_exp_f32_e32 v179, v108
	v_exp_f32_e32 v254, v109
	v_add_f32_e32 v219, v0, v219
	v_add_f32_e32 v219, v177, v219
	v_cvt_pk_fp8_f32 v252, v0, v177
	v_add_f32_e32 v219, v179, v219
	v_add_f32_e32 v219, v254, v219
	v_cvt_pk_fp8_f32 v252, v179, v254 op_sel:[0,0,1]
	s_waitcnt lgkmcnt(2)
	v_mfma_scale_f32_32x32x64_f8f6f4 v[82:97], v[122:129], v[130:137], v[82:97], v194, v193 op_sel_hi:[0,0,0]
	v_exp_f32_e32 v0, v110
	v_exp_f32_e32 v177, v111
	v_exp_f32_e32 v179, v112
	v_exp_f32_e32 v254, v113
	v_add_f32_e32 v219, v0, v219
	v_add_f32_e32 v219, v177, v219
	v_cvt_pk_fp8_f32 v253, v0, v177
	v_add_f32_e32 v219, v179, v219
	v_add_f32_e32 v219, v254, v219
	v_cvt_pk_fp8_f32 v253, v179, v254 op_sel:[0,0,1]
	ds_read_b128 v[122:125], v185 offset:43008
	ds_read_b128 v[126:129], v186 offset:43008
	ds_read_b128 v[114:117], v185 offset:45056
	ds_read_b128 v[118:121], v186 offset:45056
	ds_read_b128 v[106:109], v185 offset:47104
	ds_read_b128 v[110:113], v186 offset:47104
	ds_read_b128 v[98:101], v185 offset:49152
	ds_read_b128 v[102:105], v186 offset:49152
	s_waitcnt lgkmcnt(8)
	v_mfma_scale_f32_32x32x64_f8f6f4 v[66:81], v[222:229], v[130:137], v[66:81], v194, v193 op_sel_hi:[0,0,0]
	v_mov_b32_e32 v0, v219
	s_nop 1
	v_permlane32_swap_b32_e32 v219, v0
	v_add_f32_e32 v219, v219, v0
	v_fma_f32 v209, v209, v221, v219
	v_max_f32_e32 v177, v82, v83
	v_max3_f32 v177, v177, v84, v85
	v_max3_f32 v177, v177, v86, v87
	v_max3_f32 v177, v177, v88, v89
	v_max3_f32 v177, v177, v90, v91
	v_max3_f32 v177, v177, v92, v93
	v_max3_f32 v177, v177, v94, v95
	v_max3_f32 v177, v177, v96, v97
	s_waitcnt vmcnt(0)
	ds_write_b128 v210, v[158:161] offset:8192
	ds_write_b128 v211, v[162:165] offset:24576
	s_waitcnt lgkmcnt(8)
	v_mfma_scale_f32_32x32x64_f8f6f4 v[50:65], v[246:253], v[122:129], v[50:65], v194, v194 op_sel_hi:[0,0,0]
	s_waitcnt lgkmcnt(0)
	s_barrier
	global_load_dwordx4 v[158:161], v176, s[18:19]
	global_load_dwordx4 v[162:165], v178, s[16:17]
	v_add_u32_e32 v176, 0x2000, v176
	v_add_u32_e32 v178, 0x20000, v178
	s_waitcnt lgkmcnt(4)
	v_mfma_scale_f32_32x32x64_f8f6f4 v[34:49], v[246:253], v[114:121], v[34:49], v194, v194 op_sel_hi:[0,0,0]
	s_waitcnt lgkmcnt(2)
	v_mfma_scale_f32_32x32x64_f8f6f4 v[18:33], v[246:253], v[106:113], v[18:33], v194, v194 op_sel_hi:[0,0,0]
	s_waitcnt lgkmcnt(0)
	v_mfma_scale_f32_32x32x64_f8f6f4 v[2:17], v[246:253], v[98:105], v[2:17], v194, v194 op_sel_hi:[0,0,0]
	v_max_f32_e32 v0, v66, v67
	v_max3_f32 v0, v0, v68, v69
	v_max3_f32 v0, v0, v70, v71
	v_max3_f32 v0, v0, v72, v73
	v_max3_f32 v0, v0, v74, v75
	v_max3_f32 v0, v0, v76, v77
	v_max3_f32 v0, v0, v78, v79
	v_max3_f32 v0, v0, v80, v81
	v_max_f32_e32 v177, v177, v0
	v_mov_b32_e32 v0, v177
	v_mov_b32_e32 v218, 1.0
	s_nop 0
	v_permlane32_swap_b32_e32 v177, v0
	v_max_f32_e32 v177, v177, v0
	v_cmp_ge_f32_e32 vcc, s90, v177
	s_cmp_eq_u64 vcc, exec
	s_cbranch_scc0 .Lmla_s5_newmax
; __device__ __forceinline__ void finishSM9(f32x16& p0, f32x16& p1, float alpha, float& l_reg, v8i32& p8) {
; #pragma unroll
;   for (int r = 0; r < 16; ++r) { p0[r] = __builtin_amdgcn_exp2f(p0[r]); p1[r] = __builtin_amdgcn_exp2f(p1[r]); }
;   float ps = 0;
; #pragma unroll
;   for (int r = 0; r < 16; ++r) ps += p0[r];
; #pragma unroll
;   for (int r = 0; r < 16; ++r) ps += p1[r];
;   { auto rr = __builtin_amdgcn_permlane32_swap(__float_as_uint(ps), __float_as_uint(ps), false, false);
;     ps = __uint_as_float(rr[0]) + __uint_as_float(rr[1]); }
;   l_reg = l_reg * alpha + ps;
; #pragma unroll
;   for (int g = 0; g < 4; ++g) {
;     int w = __builtin_amdgcn_cvt_pk_fp8_f32(p0[4 * g], p0[4 * g + 1], 0, false); p8[g] = __builtin_amdgcn_cvt_pk_fp8_f32(p0[4 * g + 2], p0[4 * g + 3], w, true);
;     int u = __builtin_amdgcn_cvt_pk_fp8_f32(p1[4 * g], p1[4 * g + 1], 0, false); p8[4 + g] = __builtin_amdgcn_cvt_pk_fp8_f32(p1[4 * g + 2], p1[4 * g + 3], u, true); }
; }
; __device__ __forceinline__ void pv8(f32x16* o, const char* Vt, const v8i32 p8, int r32, int hi) {
;   const int sw = (r32 >> 2) & 3, a0 = r32 * 64 + (((hi * 2) ^ sw) << 4), a1 = r32 * 64 + (((hi * 2 + 1) ^ sw) << 4);
; #pragma unroll
;   for (int d0 = 0; d0 < 4; ++d0) {
; __device__ __forceinline__ void attn_unit7(const unsigned char* __restrict__ Q8, int ldq, const unsigned char* __restrict__ Kn8, int ldk, const unsigned char* __restrict__ Kr8, ...
;     ...
;   for (int j = 1; j + 1 < NT; j += 2) {
;     SLOAD();
;     qkt9(pB0, pB1, Kn_lds + 8192, Kr_lds + 4096, qf, 7.0f - m_reg, r32, hi);
;     finishSM9(pA0, pA1, alA, l_reg, p8);
;     pv8(o, Vt_lds, p8, r32, hi); partialSM9(pB0, pB1, m_reg, alB, thr_raw);
;     __syncthreads(); SWRITE(0);
;     RESC(alB); __syncthreads();
;     if (j + 2 < NT) SLOAD();
;     qkt9(pA0, pA1, Kn_lds, Kr_lds, qf, 7.0f - m_reg, r32, hi);
;     finishSM9(pB0, pB1, alB, l_reg, p8);
;     pv8(o, Vt_lds + 8192, p8, r32, hi); partialSM9(pA0, pA1, m_reg, alA, thr_raw);
;     __syncthreads(); if (j + 2 < NT) SWRITE(1);
;     RESC(alA); __syncthreads();
;   }
;   qkt9(pB0, pB1, Kn_lds + 8192, Kr_lds + 4096, qf, 7.0f - m_reg, r32, hi);
;   finishSM9(pA0, pA1, alA, l_reg, p8);
;   pv8(o, Vt_lds, p8, r32, hi); partialSM9(pB0, pB1, m_reg, alB, thr_raw);
;   RESC(alB);
;   finishSM9(pB0, pB1, alB, l_reg, p8);
;   pv8(o, Vt_lds + 8192, p8, r32, hi);
.Lmla_s5_cont:
	s_add_i32 s30, s30, 1
	s_cmpk_lt_u32 s30, 42
	s_cbranch_scc1 .Lmla_stag_loop
	ds_read_b128 v[114:117], v215 offset:24576
	ds_read_b128 v[118:121], v216 offset:24576
	ds_read_b128 v[222:225], v215 offset:28672
	ds_read_b128 v[226:229], v216 offset:28672
	v_exp_f32_e32 v0, v82
	v_exp_f32_e32 v177, v83
	v_exp_f32_e32 v179, v84
	v_exp_f32_e32 v254, v85
	v_add_f32_e32 v219, v0, v177
	v_cvt_pk_fp8_f32 v246, v0, v177
	v_add_f32_e32 v219, v179, v219
	v_add_f32_e32 v219, v254, v219
	v_cvt_pk_fp8_f32 v246, v179, v254 op_sel:[0,0,1]
	s_waitcnt lgkmcnt(2)
	v_mfma_scale_f32_32x32x64_f8f6f4 v[114:129], v[114:121], v[146:153], v[230:245], v194, v193 op_sel_hi:[0,0,0]
	v_exp_f32_e32 v0, v86
	v_exp_f32_e32 v177, v87
	v_exp_f32_e32 v179, v88
	v_exp_f32_e32 v254, v89
	v_add_f32_e32 v219, v0, v219
	v_add_f32_e32 v219, v177, v219
	v_cvt_pk_fp8_f32 v247, v0, v177
	v_add_f32_e32 v219, v179, v219
	v_add_f32_e32 v219, v254, v219
	v_cvt_pk_fp8_f32 v247, v179, v254 op_sel:[0,0,1]
	ds_read_b128 v[82:85], v213 offset:24576
	ds_read_b128 v[86:89], v214 offset:24576
	s_waitcnt lgkmcnt(2)
	v_mfma_scale_f32_32x32x64_f8f6f4 v[98:113], v[222:229], v[146:153], v[230:245], v194, v193 op_sel_hi:[0,0,0]
	ds_read_b128 v[222:225], v213 offset:28672
	ds_read_b128 v[226:229], v214 offset:28672
	v_exp_f32_e32 v0, v90
	v_exp_f32_e32 v177, v91
	v_exp_f32_e32 v179, v92
	v_exp_f32_e32 v254, v93
	v_add_f32_e32 v219, v0, v219
	v_add_f32_e32 v219, v177, v219
	v_cvt_pk_fp8_f32 v248, v0, v177
	v_add_f32_e32 v219, v179, v219
	v_add_f32_e32 v219, v254, v219
	v_cvt_pk_fp8_f32 v248, v179, v254 op_sel:[0,0,1]
	v_exp_f32_e32 v0, v94
	v_exp_f32_e32 v177, v95
	v_exp_f32_e32 v179, v96
	v_exp_f32_e32 v254, v97
	v_add_f32_e32 v219, v0, v219
	v_add_f32_e32 v219, v177, v219
	v_cvt_pk_fp8_f32 v249, v0, v177
	v_add_f32_e32 v219, v179, v219
	v_add_f32_e32 v219, v254, v219
	v_cvt_pk_fp8_f32 v249, v179, v254 op_sel:[0,0,1]
	ds_read_b128 v[90:93], v185 offset:36864
	ds_read_b128 v[94:97], v186 offset:36864
	s_waitcnt lgkmcnt(4)
	v_mfma_scale_f32_32x32x64_f8f6f4 v[114:129], v[82:89], v[138:145], v[114:129], v194, v193 op_sel_hi:[0,0,0]
	v_exp_f32_e32 v0, v66
	v_exp_f32_e32 v177, v67
	v_exp_f32_e32 v179, v68
	v_exp_f32_e32 v254, v69
	v_add_f32_e32 v219, v0, v219
	v_add_f32_e32 v219, v177, v219
	v_cvt_pk_fp8_f32 v250, v0, v177
	v_add_f32_e32 v219, v179, v219
	v_add_f32_e32 v219, v254, v219
	v_cvt_pk_fp8_f32 v250, v179, v254 op_sel:[0,0,1]
	s_waitcnt lgkmcnt(2)
	v_mfma_scale_f32_32x32x64_f8f6f4 v[98:113], v[222:229], v[138:145], v[98:113], v194, v193 op_sel_hi:[0,0,0]
	ds_read_b128 v[222:225], v185 offset:38912
	ds_read_b128 v[226:229], v186 offset:38912
	v_exp_f32_e32 v0, v70
	v_exp_f32_e32 v177, v71
	v_exp_f32_e32 v179, v72
	v_exp_f32_e32 v254, v73
	v_add_f32_e32 v219, v0, v219
	v_add_f32_e32 v219, v177, v219
	v_cvt_pk_fp8_f32 v251, v0, v177
	v_add_f32_e32 v219, v179, v219
	v_add_f32_e32 v219, v254, v219
	v_cvt_pk_fp8_f32 v251, v179, v254 op_sel:[0,0,1]
	v_exp_f32_e32 v0, v74
	v_exp_f32_e32 v177, v75
	v_exp_f32_e32 v179, v76
	v_exp_f32_e32 v254, v77
	v_add_f32_e32 v219, v0, v219
	v_add_f32_e32 v219, v177, v219
	v_cvt_pk_fp8_f32 v252, v0, v177
	v_add_f32_e32 v219, v179, v219
	v_add_f32_e32 v219, v254, v219
	v_cvt_pk_fp8_f32 v252, v179, v254 op_sel:[0,0,1]
	s_waitcnt lgkmcnt(2)
	v_mfma_scale_f32_32x32x64_f8f6f4 v[114:129], v[90:97], v[130:137], v[114:129], v194, v193 op_sel_hi:[0,0,0]
	v_exp_f32_e32 v0, v78
	v_exp_f32_e32 v177, v79
	v_exp_f32_e32 v179, v80
	v_exp_f32_e32 v254, v81
	v_add_f32_e32 v219, v0, v219
	v_add_f32_e32 v219, v177, v219
	v_cvt_pk_fp8_f32 v253, v0, v177
	v_add_f32_e32 v219, v179, v219
	v_add_f32_e32 v219, v254, v219
	v_cvt_pk_fp8_f32 v253, v179, v254 op_sel:[0,0,1]
	ds_read_b128 v[90:93], v185 offset:0
	ds_read_b128 v[94:97], v186 offset:0
	ds_read_b128 v[82:85], v185 offset:2048
	ds_read_b128 v[86:89], v186 offset:2048
	ds_read_b128 v[74:77], v185 offset:4096
	ds_read_b128 v[78:81], v186 offset:4096
	ds_read_b128 v[66:69], v185 offset:6144
	ds_read_b128 v[70:73], v186 offset:6144
	s_waitcnt lgkmcnt(8)
	v_mfma_scale_f32_32x32x64_f8f6f4 v[98:113], v[222:229], v[130:137], v[98:113], v194, v193 op_sel_hi:[0,0,0]
	v_mov_b32_e32 v0, v219
	s_nop 1
	v_permlane32_swap_b32_e32 v219, v0
	v_add_f32_e32 v219, v219, v0
	v_fma_f32 v209, v209, v218, v219
	v_max_f32_e32 v177, v114, v115
	v_max3_f32 v177, v177, v116, v117
	v_max3_f32 v177, v177, v118, v119
	v_max3_f32 v177, v177, v120, v121
	v_max3_f32 v177, v177, v122, v123
	v_max3_f32 v177, v177, v124, v125
	v_max3_f32 v177, v177, v126, v127
	v_max3_f32 v177, v177, v128, v129
	s_waitcnt vmcnt(0)
	ds_write_b128 v210, v[158:161] offset:43008
	ds_write_b128 v211, v[162:165] offset:51200
	s_waitcnt lgkmcnt(8)
	v_mfma_scale_f32_32x32x64_f8f6f4 v[50:65], v[246:253], v[90:97], v[50:65], v194, v194 op_sel_hi:[0,0,0]
	s_waitcnt lgkmcnt(0)
	s_barrier
	global_load_dwordx4 v[158:161], v176, s[18:19]
	global_load_dwordx4 v[162:165], v178, s[16:17]
	v_add_u32_e32 v176, 0x2000, v176
	v_add_u32_e32 v178, 0x20000, v178
	s_waitcnt lgkmcnt(4)
	v_mfma_scale_f32_32x32x64_f8f6f4 v[34:49], v[246:253], v[82:89], v[34:49], v194, v194 op_sel_hi:[0,0,0]
	s_waitcnt lgkmcnt(2)
	v_mfma_scale_f32_32x32x64_f8f6f4 v[18:33], v[246:253], v[74:81], v[18:33], v194, v194 op_sel_hi:[0,0,0]
	s_waitcnt lgkmcnt(0)
	v_mfma_scale_f32_32x32x64_f8f6f4 v[2:17], v[246:253], v[66:73], v[2:17], v194, v194 op_sel_hi:[0,0,0]
	v_max_f32_e32 v0, v98, v99
	v_max3_f32 v0, v0, v100, v101
	v_max3_f32 v0, v0, v102, v103
	v_max3_f32 v0, v0, v104, v105
	v_max3_f32 v0, v0, v106, v107
	v_max3_f32 v0, v0, v108, v109
	v_max3_f32 v0, v0, v110, v111
	v_max3_f32 v0, v0, v112, v113
	v_max_f32_e32 v177, v177, v0
	v_mov_b32_e32 v0, v177
	v_mov_b32_e32 v221, 1.0
	s_nop 0
	v_permlane32_swap_b32_e32 v177, v0
	v_max_f32_e32 v177, v177, v0
	v_cmp_ge_f32_e32 vcc, s90, v177
	s_cmp_eq_u64 vcc, exec
	s_cbranch_scc0 .Lmla_q0_newmax
; __device__ __forceinline__ v8i32 cat8(v4i32 a, v4i32 b) { return (v8i32){a[0], a[1], a[2], a[3], b[0], b[1], b[2], b[3]}; }
; __device__ __forceinline__ void finishSM9(f32x16& p0, f32x16& p1, float alpha, float& l_reg, v8i32& p8) {
; #pragma unroll
;   for (int r = 0; r < 16; ++r) { p0[r] = __builtin_amdgcn_exp2f(p0[r]); p1[r] = __builtin_amdgcn_exp2f(p1[r]); }
;   float ps = 0;
; #pragma unroll
;   for (int r = 0; r < 16; ++r) ps += p0[r];
; #pragma unroll
;   for (int r = 0; r < 16; ++r) ps += p1[r];
;   { auto rr = __builtin_amdgcn_permlane32_swap(__float_as_uint(ps), __float_as_uint(ps), false, false);
;     ps = __uint_as_float(rr[0]) + __uint_as_float(rr[1]); }
;   l_reg = l_reg * alpha + ps;
; #pragma unroll
;   for (int g = 0; g < 4; ++g) {
;     int w = __builtin_amdgcn_cvt_pk_fp8_f32(p0[4 * g], p0[4 * g + 1], 0, false); p8[g] = __builtin_amdgcn_cvt_pk_fp8_f32(p0[4 * g + 2], p0[4 * g + 3], w, true);
;     int u = __builtin_amdgcn_cvt_pk_fp8_f32(p1[4 * g], p1[4 * g + 1], 0, false); p8[4 + g] = __builtin_amdgcn_cvt_pk_fp8_f32(p1[4 * g + 2], p1[4 * g + 3], u, true); }
; }
; __device__ __forceinline__ void pv8(f32x16* o, const char* Vt, const v8i32 p8, int r32, int hi) {
;   const int sw = (r32 >> 2) & 3, a0 = r32 * 64 + (((hi * 2) ^ sw) << 4), a1 = r32 * 64 + (((hi * 2 + 1) ^ sw) << 4);
; #pragma unroll
;   for (int d0 = 0; d0 < 4; ++d0) {
;     const v8i32 vf = cat8(*reinterpret_cast<const v4i32*>(Vt + d0 * 2048 + a0), *reinterpret_cast<const v4i32*>(Vt + d0 * 2048 + a1));
;     o[d0] = __builtin_amdgcn_mfma_scale_f32_32x32x64_f8f6f4(p8, vf, o[d0], 0, 0, 0, 127, 0, 127); }
; }
; __device__ __forceinline__ void qkt9(f32x16& p0, f32x16& p1, const char* Kn, const char* Kr, const v8i32* qf, const float init, int r32, int hi) {
; #pragma unroll
;   for (int r = 0; r < 16; ++r) { p0[r] = init; p1[r] = init; }
; #pragma unroll
;   for (int s = 0; s < 2; ++s) { const int c0 = s * 4 + hi * 2;
; __device__ __forceinline__ void attn_unit7(const unsigned char* __restrict__ Q8, int ldq, const unsigned char* __restrict__ Kn8, int ldk, const unsigned char* __restrict__ Kr8, ...
;     ...
;   qkt9(pB0, pB1, Kn_lds + 8192, Kr_lds + 4096, qf, 7.0f - m_reg, r32, hi);
;   finishSM9(pA0, pA1, alA, l_reg, p8);
;   pv8(o, Vt_lds, p8, r32, hi); partialSM9(pB0, pB1, m_reg, alB, thr_raw);
;   RESC(alB);
;   finishSM9(pB0, pB1, alB, l_reg, p8);
;   pv8(o, Vt_lds + 8192, p8, r32, hi);
.Lmla_q0_cont:
	ds_read_b128 v[82:85], v215 offset:51200
	ds_read_b128 v[86:89], v216 offset:51200
	ds_read_b128 v[222:225], v215 offset:55296
	ds_read_b128 v[226:229], v216 offset:55296
	v_exp_f32_e32 v0, v114
	v_exp_f32_e32 v177, v115
	v_exp_f32_e32 v179, v116
	v_exp_f32_e32 v254, v117
	v_add_f32_e32 v219, v0, v177
	v_cvt_pk_fp8_f32 v246, v0, v177
	v_add_f32_e32 v219, v179, v219
	v_add_f32_e32 v219, v254, v219
	v_cvt_pk_fp8_f32 v246, v179, v254 op_sel:[0,0,1]
	s_waitcnt lgkmcnt(2)
	v_mfma_scale_f32_32x32x64_f8f6f4 v[82:97], v[82:89], v[146:153], v[230:245], v194, v193 op_sel_hi:[0,0,0]
	v_exp_f32_e32 v0, v118
	v_exp_f32_e32 v177, v119
	v_exp_f32_e32 v179, v120
	v_exp_f32_e32 v254, v121
	v_add_f32_e32 v219, v0, v219
	v_add_f32_e32 v219, v177, v219
	v_cvt_pk_fp8_f32 v247, v0, v177
	v_add_f32_e32 v219, v179, v219
	v_add_f32_e32 v219, v254, v219
	v_cvt_pk_fp8_f32 v247, v179, v254 op_sel:[0,0,1]
	ds_read_b128 v[114:117], v213 offset:51200
	ds_read_b128 v[118:121], v214 offset:51200
	s_waitcnt lgkmcnt(2)
	v_mfma_scale_f32_32x32x64_f8f6f4 v[66:81], v[222:229], v[146:153], v[230:245], v194, v193 op_sel_hi:[0,0,0]
	ds_read_b128 v[222:225], v213 offset:55296
	ds_read_b128 v[226:229], v214 offset:55296
	v_exp_f32_e32 v0, v122
	v_exp_f32_e32 v177, v123
	v_exp_f32_e32 v179, v124
	v_exp_f32_e32 v254, v125
	v_add_f32_e32 v219, v0, v219
	v_add_f32_e32 v219, v177, v219
	v_cvt_pk_fp8_f32 v248, v0, v177
	v_add_f32_e32 v219, v179, v219
	v_add_f32_e32 v219, v254, v219
	v_cvt_pk_fp8_f32 v248, v179, v254 op_sel:[0,0,1]
	v_exp_f32_e32 v0, v126
	v_exp_f32_e32 v177, v127
	v_exp_f32_e32 v179, v128
	v_exp_f32_e32 v254, v129
	v_add_f32_e32 v219, v0, v219
	v_add_f32_e32 v219, v177, v219
	v_cvt_pk_fp8_f32 v249, v0, v177
	v_add_f32_e32 v219, v179, v219
	v_add_f32_e32 v219, v254, v219
	v_cvt_pk_fp8_f32 v249, v179, v254 op_sel:[0,0,1]
	ds_read_b128 v[122:125], v185 offset:59392
	ds_read_b128 v[126:129], v186 offset:59392
	s_waitcnt lgkmcnt(4)
	v_mfma_scale_f32_32x32x64_f8f6f4 v[82:97], v[114:121], v[138:145], v[82:97], v194, v193 op_sel_hi:[0,0,0]
	v_exp_f32_e32 v0, v98
	v_exp_f32_e32 v177, v99
	v_exp_f32_e32 v179, v100
	v_exp_f32_e32 v254, v101
	v_add_f32_e32 v219, v0, v219
	v_add_f32_e32 v219, v177, v219
	v_cvt_pk_fp8_f32 v250, v0, v177
	v_add_f32_e32 v219, v179, v219
	v_add_f32_e32 v219, v254, v219
	v_cvt_pk_fp8_f32 v250, v179, v254 op_sel:[0,0,1]
	s_waitcnt lgkmcnt(2)
	v_mfma_scale_f32_32x32x64_f8f6f4 v[66:81], v[222:229], v[138:145], v[66:81], v194, v193 op_sel_hi:[0,0,0]
	ds_read_b128 v[222:225], v185 offset:61440
	ds_read_b128 v[226:229], v186 offset:61440
	v_exp_f32_e32 v0, v102
	v_exp_f32_e32 v177, v103
	v_exp_f32_e32 v179, v104
	v_exp_f32_e32 v254, v105
	v_add_f32_e32 v219, v0, v219
	v_add_f32_e32 v219, v177, v219
	v_cvt_pk_fp8_f32 v251, v0, v177
	v_add_f32_e32 v219, v179, v219
	v_add_f32_e32 v219, v254, v219
	v_cvt_pk_fp8_f32 v251, v179, v254 op_sel:[0,0,1]
	v_exp_f32_e32 v0, v106
	v_exp_f32_e32 v177, v107
	v_exp_f32_e32 v179, v108
	v_exp_f32_e32 v254, v109
	v_add_f32_e32 v219, v0, v219
	v_add_f32_e32 v219, v177, v219
	v_cvt_pk_fp8_f32 v252, v0, v177
	v_add_f32_e32 v219, v179, v219
	v_add_f32_e32 v219, v254, v219
	v_cvt_pk_fp8_f32 v252, v179, v254 op_sel:[0,0,1]
	s_waitcnt lgkmcnt(2)
	v_mfma_scale_f32_32x32x64_f8f6f4 v[82:97], v[122:129], v[130:137], v[82:97], v194, v193 op_sel_hi:[0,0,0]
	v_exp_f32_e32 v0, v110
	v_exp_f32_e32 v177, v111
	v_exp_f32_e32 v179, v112
	v_exp_f32_e32 v254, v113
	v_add_f32_e32 v219, v0, v219
	v_add_f32_e32 v219, v177, v219
	v_cvt_pk_fp8_f32 v253, v0, v177
	v_add_f32_e32 v219, v179, v219
	v_add_f32_e32 v219, v254, v219
	v_cvt_pk_fp8_f32 v253, v179, v254 op_sel:[0,0,1]
	ds_read_b128 v[122:125], v185 offset:8192
	ds_read_b128 v[126:129], v186 offset:8192
	ds_read_b128 v[114:117], v185 offset:10240
	ds_read_b128 v[118:121], v186 offset:10240
	ds_read_b128 v[106:109], v185 offset:12288
	ds_read_b128 v[110:113], v186 offset:12288
	ds_read_b128 v[98:101], v185 offset:14336
	ds_read_b128 v[102:105], v186 offset:14336
	s_waitcnt lgkmcnt(8)
	v_mfma_scale_f32_32x32x64_f8f6f4 v[66:81], v[222:229], v[130:137], v[66:81], v194, v193 op_sel_hi:[0,0,0]
	v_mov_b32_e32 v0, v219
	s_nop 1
	v_permlane32_swap_b32_e32 v219, v0
	v_add_f32_e32 v219, v219, v0
	v_fma_f32 v209, v209, v221, v219
	v_max_f32_e32 v177, v82, v83
	v_max3_f32 v177, v177, v84, v85
	v_max3_f32 v177, v177, v86, v87
	v_max3_f32 v177, v177, v88, v89
	v_max3_f32 v177, v177, v90, v91
	v_max3_f32 v177, v177, v92, v93
	v_max3_f32 v177, v177, v94, v95
	v_max3_f32 v177, v177, v96, v97
	s_waitcnt vmcnt(0)
	ds_write_b128 v210, v[158:161]
	ds_write_b128 v211, v[162:165] offset:16384
	s_waitcnt lgkmcnt(8)
	v_mfma_scale_f32_32x32x64_f8f6f4 v[50:65], v[246:253], v[122:129], v[50:65], v194, v194 op_sel_hi:[0,0,0]
	s_waitcnt lgkmcnt(0)
	s_barrier
	s_waitcnt lgkmcnt(4)
	v_mfma_scale_f32_32x32x64_f8f6f4 v[34:49], v[246:253], v[114:121], v[34:49], v194, v194 op_sel_hi:[0,0,0]
	s_waitcnt lgkmcnt(2)
	v_mfma_scale_f32_32x32x64_f8f6f4 v[18:33], v[246:253], v[106:113], v[18:33], v194, v194 op_sel_hi:[0,0,0]
	s_waitcnt lgkmcnt(0)
	v_mfma_scale_f32_32x32x64_f8f6f4 v[2:17], v[246:253], v[98:105], v[2:17], v194, v194 op_sel_hi:[0,0,0]
	v_max_f32_e32 v0, v66, v67
	v_max3_f32 v0, v0, v68, v69
	v_max3_f32 v0, v0, v70, v71
	v_max3_f32 v0, v0, v72, v73
	v_max3_f32 v0, v0, v74, v75
	v_max3_f32 v0, v0, v76, v77
	v_max3_f32 v0, v0, v78, v79
	v_max3_f32 v0, v0, v80, v81
	v_max_f32_e32 v177, v177, v0
	v_mov_b32_e32 v0, v177
	v_mov_b32_e32 v218, 1.0
	s_nop 0
	v_permlane32_swap_b32_e32 v177, v0
	v_max_f32_e32 v177, v177, v0
	v_cmp_ge_f32_e32 vcc, s90, v177
	s_cmp_eq_u64 vcc, exec
	s_cbranch_scc0 .Lmla_q1_newmax
